# K-loops: the four B-fragment LDS read bases share one VGPR (buffer distance in the ds_read offset), 3 fewer VALU per iteration
# speedup vs baseline: 1.0174x; 1.0017x over previous
.LBB0_108:
	s_add_u32 s26, s50, 0xfff80080
	s_addc_u32 s27, s51, -1
	s_add_i32 s67, 0, 0x10000
	v_add_u32_e32 v134, s67, v180
	ds_read_b128 v[182:185], v134
	ds_read_b128 v[186:189], v134 offset:1024
	ds_read_b128 v[190:193], v134 offset:2048
	ds_read_b128 v[194:197], v134 offset:3072
	s_cmp_eq_u32 s66, 28
	s_cselect_b32 s53, s43, s27
	s_cselect_b32 s52, s62, s26
	s_cselect_b32 s27, s23, s65
	s_cselect_b32 s26, s63, s64
	s_add_i32 m0, s7, 0xc000
	ds_read_b128 v[198:201], v181
	ds_read_b128 v[202:205], v181 offset:1024
	ds_read_b128 v[206:209], v181 offset:2048
	ds_read_b128 v[210:213], v181 offset:3072
	ds_read_b128 v[214:217], v181 offset:4096
	ds_read_b128 v[218:221], v181 offset:5120
	ds_read_b128 v[222:225], v181 offset:6144
	ds_read_b128 v[226:229], v181 offset:7168
	global_load_lds_dwordx4 v162, s[50:51]
	s_add_i32 m0, s7, 0xe000
	s_nop 0
	global_load_lds_dwordx4 v164, s[50:51]
	s_waitcnt lgkmcnt(8)
	s_barrier
	s_waitcnt lgkmcnt(0)
	s_setprio 1
	s_waitcnt lgkmcnt(0)
	v_mfma_f32_16x16x32_bf16 v[126:129], v[182:185], v[198:201], v[126:129]
	v_mfma_f32_16x16x32_bf16 v[118:121], v[190:193], v[198:201], v[118:121]
	v_mfma_f32_16x16x32_bf16 v[110:113], v[182:185], v[206:209], v[110:113]
	v_mfma_f32_16x16x32_bf16 v[102:105], v[190:193], v[206:209], v[102:105]
	v_mfma_f32_16x16x32_bf16 v[94:97], v[182:185], v[214:217], v[94:97]
	v_mfma_f32_16x16x32_bf16 v[86:89], v[190:193], v[214:217], v[86:89]
	v_mfma_f32_16x16x32_bf16 v[78:81], v[182:185], v[222:225], v[78:81]
	v_mfma_f32_16x16x32_bf16 v[70:73], v[190:193], v[222:225], v[70:73]
	v_mfma_f32_16x16x32_bf16 v[126:129], v[186:189], v[202:205], v[126:129]
	v_mfma_f32_16x16x32_bf16 v[118:121], v[194:197], v[202:205], v[118:121]
	v_mfma_f32_16x16x32_bf16 v[110:113], v[186:189], v[210:213], v[110:113]
	v_mfma_f32_16x16x32_bf16 v[102:105], v[194:197], v[210:213], v[102:105]
	v_mfma_f32_16x16x32_bf16 v[94:97], v[186:189], v[218:221], v[94:97]
	v_mfma_f32_16x16x32_bf16 v[86:89], v[194:197], v[218:221], v[86:89]
	v_mfma_f32_16x16x32_bf16 v[78:81], v[186:189], v[226:229], v[78:81]
	v_mfma_f32_16x16x32_bf16 v[70:73], v[194:197], v[226:229], v[70:73]
	s_setprio 0
	s_barrier
	s_add_i32 s70, 0, 0x14000
	s_add_i32 s67, s67, s6
	s_mov_b32 m0, s67
	ds_read_b128 v[230:233], v134 offset:16384
	ds_read_b128 v[234:237], v134 offset:17408
	ds_read_b128 v[238:241], v134 offset:18432
	ds_read_b128 v[242:245], v134 offset:19456
	global_load_lds_dwordx4 v0, s[26:27]
	s_add_i32 m0, s67, 0x2000
	s_nop 0
	global_load_lds_dwordx4 v138, s[26:27]
	s_barrier
	s_waitcnt lgkmcnt(0)
	s_setprio 1
	s_waitcnt lgkmcnt(0)
	v_mfma_f32_16x16x32_bf16 v[122:125], v[230:233], v[198:201], v[122:125]
	v_mfma_f32_16x16x32_bf16 v[114:117], v[238:241], v[198:201], v[114:117]
	v_mfma_f32_16x16x32_bf16 v[106:109], v[230:233], v[206:209], v[106:109]
	v_mfma_f32_16x16x32_bf16 v[98:101], v[238:241], v[206:209], v[98:101]
	v_mfma_f32_16x16x32_bf16 v[90:93], v[230:233], v[214:217], v[90:93]
	v_mfma_f32_16x16x32_bf16 v[82:85], v[238:241], v[214:217], v[82:85]
	v_mfma_f32_16x16x32_bf16 v[74:77], v[230:233], v[222:225], v[74:77]
	v_mfma_f32_16x16x32_bf16 v[66:69], v[238:241], v[222:225], v[66:69]
	v_mfma_f32_16x16x32_bf16 v[122:125], v[234:237], v[202:205], v[122:125]
	v_mfma_f32_16x16x32_bf16 v[114:117], v[242:245], v[202:205], v[114:117]
	v_mfma_f32_16x16x32_bf16 v[106:109], v[234:237], v[210:213], v[106:109]
	v_mfma_f32_16x16x32_bf16 v[98:101], v[242:245], v[210:213], v[98:101]
	v_mfma_f32_16x16x32_bf16 v[90:93], v[234:237], v[218:221], v[90:93]
	v_mfma_f32_16x16x32_bf16 v[82:85], v[242:245], v[218:221], v[82:85]
	v_mfma_f32_16x16x32_bf16 v[74:77], v[234:237], v[226:229], v[74:77]
	v_mfma_f32_16x16x32_bf16 v[66:69], v[242:245], v[226:229], v[66:69]
	s_setprio 0
	s_mov_b32 m0, s7
	s_add_u32 vcc_lo, s52, s10
	s_addc_u32 vcc_hi, s53, s11
	s_barrier
	ds_read_b128 v[198:201], v181 offset:16384
	ds_read_b128 v[202:205], v181 offset:17408
	ds_read_b128 v[206:209], v181 offset:18432
	ds_read_b128 v[210:213], v181 offset:19456
	ds_read_b128 v[214:217], v181 offset:20480
	ds_read_b128 v[218:221], v181 offset:21504
	ds_read_b128 v[222:225], v181 offset:22528
	ds_read_b128 v[226:229], v181 offset:23552
	global_load_lds_dwordx4 v142, s[52:53]
	s_mov_b32 m0, s14
	s_nop 0
	global_load_lds_dwordx4 v140, s[52:53]
	s_barrier
	s_waitcnt lgkmcnt(0)
	s_setprio 1
	s_waitcnt lgkmcnt(0)
	v_mfma_f32_16x16x32_bf16 v[62:65], v[182:185], v[198:201], v[62:65]
	v_mfma_f32_16x16x32_bf16 v[54:57], v[190:193], v[198:201], v[54:57]
	v_mfma_f32_16x16x32_bf16 v[46:49], v[182:185], v[206:209], v[46:49]
	v_mfma_f32_16x16x32_bf16 v[38:41], v[190:193], v[206:209], v[38:41]
	v_mfma_f32_16x16x32_bf16 v[30:33], v[182:185], v[214:217], v[30:33]
	v_mfma_f32_16x16x32_bf16 v[22:25], v[190:193], v[214:217], v[22:25]
	v_mfma_f32_16x16x32_bf16 v[14:17], v[182:185], v[222:225], v[14:17]
	v_mfma_f32_16x16x32_bf16 v[6:9], v[190:193], v[222:225], v[6:9]
	v_mfma_f32_16x16x32_bf16 v[62:65], v[186:189], v[202:205], v[62:65]
	v_mfma_f32_16x16x32_bf16 v[54:57], v[194:197], v[202:205], v[54:57]
	v_mfma_f32_16x16x32_bf16 v[46:49], v[186:189], v[210:213], v[46:49]
	v_mfma_f32_16x16x32_bf16 v[38:41], v[194:197], v[210:213], v[38:41]
	v_mfma_f32_16x16x32_bf16 v[30:33], v[186:189], v[218:221], v[30:33]
	v_mfma_f32_16x16x32_bf16 v[22:25], v[194:197], v[218:221], v[22:25]
	v_mfma_f32_16x16x32_bf16 v[14:17], v[186:189], v[226:229], v[14:17]
	v_mfma_f32_16x16x32_bf16 v[6:9], v[194:197], v[226:229], v[6:9]
	s_setprio 0
	s_barrier
	s_add_u32 s68, s26, 0x80000
	s_addc_u32 s69, s27, 0
	s_add_i32 s67, s70, s6
	s_mov_b32 m0, s67
	s_nop 0
	global_load_lds_dwordx4 v0, s[68:69]
	s_add_i32 m0, s67, 0x2000
	s_nop 0
	global_load_lds_dwordx4 v138, s[68:69]
	s_waitcnt vmcnt(6)
	s_barrier
	s_setprio 1
	v_mfma_f32_16x16x32_bf16 v[58:61], v[230:233], v[198:201], v[58:61]
	v_mfma_f32_16x16x32_bf16 v[50:53], v[238:241], v[198:201], v[50:53]
	v_mfma_f32_16x16x32_bf16 v[42:45], v[230:233], v[206:209], v[42:45]
	v_mfma_f32_16x16x32_bf16 v[34:37], v[238:241], v[206:209], v[34:37]
	v_mfma_f32_16x16x32_bf16 v[26:29], v[230:233], v[214:217], v[26:29]
	v_mfma_f32_16x16x32_bf16 v[18:21], v[238:241], v[214:217], v[18:21]
	v_mfma_f32_16x16x32_bf16 v[10:13], v[230:233], v[222:225], v[10:13]
	v_mfma_f32_16x16x32_bf16 v[2:5], v[238:241], v[222:225], v[2:5]
	v_mfma_f32_16x16x32_bf16 v[58:61], v[234:237], v[202:205], v[58:61]
	v_mfma_f32_16x16x32_bf16 v[50:53], v[242:245], v[202:205], v[50:53]
	v_mfma_f32_16x16x32_bf16 v[42:45], v[234:237], v[210:213], v[42:45]
	v_mfma_f32_16x16x32_bf16 v[34:37], v[242:245], v[210:213], v[34:37]
	v_mfma_f32_16x16x32_bf16 v[26:29], v[234:237], v[218:221], v[26:29]
	v_mfma_f32_16x16x32_bf16 v[18:21], v[242:245], v[218:221], v[18:21]
	v_mfma_f32_16x16x32_bf16 v[10:13], v[234:237], v[226:229], v[10:13]
	v_mfma_f32_16x16x32_bf16 v[2:5], v[242:245], v[226:229], v[2:5]
	s_setprio 0
	s_add_i32 s67, 0, 0x18000
	s_barrier
	ds_read_b128 v[182:185], v134 offset:32768
	ds_read_b128 v[186:189], v134 offset:33792
	ds_read_b128 v[190:193], v134 offset:34816
	ds_read_b128 v[194:197], v134 offset:35840
	s_add_u32 s52, s52, 0x80000
	s_addc_u32 s53, s53, 0
	s_mov_b32 m0, s54
	ds_read_b128 v[198:201], v181 offset:32768
	ds_read_b128 v[202:205], v181 offset:33792
	ds_read_b128 v[206:209], v181 offset:34816
	ds_read_b128 v[210:213], v181 offset:35840
	ds_read_b128 v[214:217], v181 offset:36864
	ds_read_b128 v[218:221], v181 offset:37888
	ds_read_b128 v[222:225], v181 offset:38912
	ds_read_b128 v[226:229], v181 offset:39936
	global_load_lds_dwordx4 v142, s[52:53]
	s_mov_b32 m0, s55
	s_nop 0
	global_load_lds_dwordx4 v140, s[52:53]
	s_waitcnt lgkmcnt(8)
	s_barrier
	s_waitcnt lgkmcnt(0)
	s_setprio 1
	s_waitcnt lgkmcnt(0)
	v_mfma_f32_16x16x32_bf16 v[126:129], v[182:185], v[198:201], v[126:129]
	v_mfma_f32_16x16x32_bf16 v[118:121], v[190:193], v[198:201], v[118:121]
	v_mfma_f32_16x16x32_bf16 v[110:113], v[182:185], v[206:209], v[110:113]
	v_mfma_f32_16x16x32_bf16 v[102:105], v[190:193], v[206:209], v[102:105]
	v_mfma_f32_16x16x32_bf16 v[94:97], v[182:185], v[214:217], v[94:97]
	v_mfma_f32_16x16x32_bf16 v[86:89], v[190:193], v[214:217], v[86:89]
	v_mfma_f32_16x16x32_bf16 v[78:81], v[182:185], v[222:225], v[78:81]
	v_mfma_f32_16x16x32_bf16 v[70:73], v[190:193], v[222:225], v[70:73]
	v_mfma_f32_16x16x32_bf16 v[126:129], v[186:189], v[202:205], v[126:129]
	v_mfma_f32_16x16x32_bf16 v[118:121], v[194:197], v[202:205], v[118:121]
	v_mfma_f32_16x16x32_bf16 v[110:113], v[186:189], v[210:213], v[110:113]
	v_mfma_f32_16x16x32_bf16 v[102:105], v[194:197], v[210:213], v[102:105]
	v_mfma_f32_16x16x32_bf16 v[94:97], v[186:189], v[218:221], v[94:97]
	v_mfma_f32_16x16x32_bf16 v[86:89], v[194:197], v[218:221], v[86:89]
	v_mfma_f32_16x16x32_bf16 v[78:81], v[186:189], v[226:229], v[78:81]
	v_mfma_f32_16x16x32_bf16 v[70:73], v[194:197], v[226:229], v[70:73]
	s_setprio 0
	s_barrier
	s_add_i32 s52, 0, 0x1c000
	s_add_i32 s53, s67, s6
	s_add_u32 s100, s26, s10
	s_addc_u32 s101, s27, s11
	s_mov_b32 m0, s53
	ds_read_b128 v[230:233], v134 offset:49152
	ds_read_b128 v[234:237], v134 offset:50176
	ds_read_b128 v[238:241], v134 offset:51200
	ds_read_b128 v[242:245], v134 offset:52224
	global_load_lds_dwordx4 v0, s[100:101]
	s_add_u32 s100, s26, s10
	s_addc_u32 s101, s27, s11
	s_add_i32 m0, s53, 0x2000
	s_nop 0
	global_load_lds_dwordx4 v138, s[100:101]
	s_barrier
	s_waitcnt lgkmcnt(0)
	s_setprio 1
	s_waitcnt lgkmcnt(0)
	v_mfma_f32_16x16x32_bf16 v[122:125], v[230:233], v[198:201], v[122:125]
	v_mfma_f32_16x16x32_bf16 v[114:117], v[238:241], v[198:201], v[114:117]
	v_mfma_f32_16x16x32_bf16 v[106:109], v[230:233], v[206:209], v[106:109]
	v_mfma_f32_16x16x32_bf16 v[98:101], v[238:241], v[206:209], v[98:101]
	v_mfma_f32_16x16x32_bf16 v[90:93], v[230:233], v[214:217], v[90:93]
	v_mfma_f32_16x16x32_bf16 v[82:85], v[238:241], v[214:217], v[82:85]
	v_mfma_f32_16x16x32_bf16 v[74:77], v[230:233], v[222:225], v[74:77]
	v_mfma_f32_16x16x32_bf16 v[66:69], v[238:241], v[222:225], v[66:69]
	v_mfma_f32_16x16x32_bf16 v[122:125], v[234:237], v[202:205], v[122:125]
	v_mfma_f32_16x16x32_bf16 v[114:117], v[242:245], v[202:205], v[114:117]
	v_mfma_f32_16x16x32_bf16 v[106:109], v[234:237], v[210:213], v[106:109]
	v_mfma_f32_16x16x32_bf16 v[98:101], v[242:245], v[210:213], v[98:101]
	v_mfma_f32_16x16x32_bf16 v[90:93], v[234:237], v[218:221], v[90:93]
	v_mfma_f32_16x16x32_bf16 v[82:85], v[242:245], v[218:221], v[82:85]
	v_mfma_f32_16x16x32_bf16 v[74:77], v[234:237], v[226:229], v[74:77]
	v_mfma_f32_16x16x32_bf16 v[66:69], v[242:245], v[226:229], v[66:69]
	s_setprio 0
	s_mov_b32 m0, s57
	s_barrier
	ds_read_b128 v[198:201], v181 offset:49152
	ds_read_b128 v[202:205], v181 offset:50176
	ds_read_b128 v[206:209], v181 offset:51200
	ds_read_b128 v[210:213], v181 offset:52224
	ds_read_b128 v[214:217], v181 offset:53248
	ds_read_b128 v[218:221], v181 offset:54272
	ds_read_b128 v[222:225], v181 offset:55296
	ds_read_b128 v[226:229], v181 offset:56320
	global_load_lds_dwordx4 v142, vcc
	s_mov_b32 m0, s58
	s_nop 0
	global_load_lds_dwordx4 v140, vcc
	s_barrier
	s_waitcnt lgkmcnt(0)
	s_setprio 1
	s_waitcnt lgkmcnt(0)
	v_mfma_f32_16x16x32_bf16 v[62:65], v[182:185], v[198:201], v[62:65]
	v_mfma_f32_16x16x32_bf16 v[54:57], v[190:193], v[198:201], v[54:57]
	v_mfma_f32_16x16x32_bf16 v[46:49], v[182:185], v[206:209], v[46:49]
	v_mfma_f32_16x16x32_bf16 v[38:41], v[190:193], v[206:209], v[38:41]
	v_mfma_f32_16x16x32_bf16 v[30:33], v[182:185], v[214:217], v[30:33]
	v_mfma_f32_16x16x32_bf16 v[22:25], v[190:193], v[214:217], v[22:25]
	v_mfma_f32_16x16x32_bf16 v[14:17], v[182:185], v[222:225], v[14:17]
	v_mfma_f32_16x16x32_bf16 v[6:9], v[190:193], v[222:225], v[6:9]
	v_mfma_f32_16x16x32_bf16 v[62:65], v[186:189], v[202:205], v[62:65]
	v_mfma_f32_16x16x32_bf16 v[54:57], v[194:197], v[202:205], v[54:57]
	v_mfma_f32_16x16x32_bf16 v[46:49], v[186:189], v[210:213], v[46:49]
	v_mfma_f32_16x16x32_bf16 v[38:41], v[194:197], v[210:213], v[38:41]
	v_mfma_f32_16x16x32_bf16 v[30:33], v[186:189], v[218:221], v[30:33]
	v_mfma_f32_16x16x32_bf16 v[22:25], v[194:197], v[218:221], v[22:25]
	v_mfma_f32_16x16x32_bf16 v[14:17], v[186:189], v[226:229], v[14:17]
	v_mfma_f32_16x16x32_bf16 v[6:9], v[194:197], v[226:229], v[6:9]
	s_setprio 0
	s_barrier
	s_add_u32 s26, s26, 0x80080
	s_addc_u32 s27, s27, 0
	s_add_i32 s52, s52, s6
	s_mov_b32 m0, s52
	s_nop 0
	global_load_lds_dwordx4 v0, s[26:27]
	s_add_i32 m0, s52, 0x2000
	s_nop 0
	global_load_lds_dwordx4 v138, s[26:27]
	s_waitcnt vmcnt(6)
	s_barrier
	s_setprio 1
	v_mfma_f32_16x16x32_bf16 v[58:61], v[230:233], v[198:201], v[58:61]
	v_mfma_f32_16x16x32_bf16 v[50:53], v[238:241], v[198:201], v[50:53]
	v_mfma_f32_16x16x32_bf16 v[42:45], v[230:233], v[206:209], v[42:45]
	v_mfma_f32_16x16x32_bf16 v[34:37], v[238:241], v[206:209], v[34:37]
	v_mfma_f32_16x16x32_bf16 v[26:29], v[230:233], v[214:217], v[26:29]
	v_mfma_f32_16x16x32_bf16 v[18:21], v[238:241], v[214:217], v[18:21]
	v_mfma_f32_16x16x32_bf16 v[10:13], v[230:233], v[222:225], v[10:13]
	v_mfma_f32_16x16x32_bf16 v[2:5], v[238:241], v[222:225], v[2:5]
	v_mfma_f32_16x16x32_bf16 v[58:61], v[234:237], v[202:205], v[58:61]
	v_mfma_f32_16x16x32_bf16 v[50:53], v[242:245], v[202:205], v[50:53]
	v_mfma_f32_16x16x32_bf16 v[42:45], v[234:237], v[210:213], v[42:45]
	v_mfma_f32_16x16x32_bf16 v[34:37], v[242:245], v[210:213], v[34:37]
	v_mfma_f32_16x16x32_bf16 v[26:29], v[234:237], v[218:221], v[26:29]
	v_mfma_f32_16x16x32_bf16 v[18:21], v[242:245], v[218:221], v[18:21]
	v_mfma_f32_16x16x32_bf16 v[10:13], v[234:237], v[226:229], v[10:13]
	v_mfma_f32_16x16x32_bf16 v[2:5], v[242:245], v[226:229], v[2:5]
	s_setprio 0
	s_add_i32 s66, s66, 2
	s_add_u32 s50, s50, 0x100
	s_addc_u32 s51, s51, 0
	s_add_u32 s64, s64, 0x100
	s_addc_u32 s65, s65, 0
	s_cmp_gt_u32 s66, 29
	s_barrier
	s_cbranch_scc0 .LBB0_108
	v_mul_f32_e32 v134, 0xbfb8aa3b, v126
	v_exp_f32_e32 v134, v134
	s_lshl_b32 s23, s61, 7
	s_or_b32 s23, s23, s56
	s_ashr_i32 s23, s23, 6
	v_add_f32_e32 v134, 1.0, v134
	v_rcp_f32_e32 v134, v134
	s_mul_i32 s26, s60, 0x58
	s_ashr_i32 s43, s23, 31
	s_mul_hi_i32 s27, s60, 0x58
	v_mul_f32_e32 v126, v126, v134
	v_mul_f32_e32 v122, v126, v122
	v_mul_f32_e32 v126, 0xbfb8aa3b, v118
	v_exp_f32_e32 v126, v126
	s_add_u32 s26, s26, s23
	s_addc_u32 s27, s27, s43
	s_lshl_b64 s[26:27], s[26:27], 15
	v_add_f32_e32 v126, 1.0, v126
	v_rcp_f32_e32 v126, v126
	v_lshl_add_u64 v[166:167], v[144:145], 0, s[26:27]
	s_and_b64 vcc, exec, s[38:39]
	s_mov_b32 s61, s22
	v_mul_f32_e32 v118, v118, v126
	v_mul_f32_e32 v126, v118, v114
	v_mul_f32_e32 v114, 0xbfb8aa3b, v127
	v_mul_f32_e32 v118, 0xbfb8aa3b, v119
	v_exp_f32_e32 v114, v114
	v_exp_f32_e32 v118, v118
	s_mov_b32 s60, s42
	s_mov_b64 s[26:27], s[24:25]
	v_add_f32_e32 v114, 1.0, v114
	v_add_f32_e32 v118, 1.0, v118
	v_rcp_f32_e32 v114, v114
	v_rcp_f32_e32 v118, v118
	s_mov_b64 s[50:51], s[48:49]
	v_readlane_b32 s70, v254, 38
	v_mul_f32_e32 v114, v127, v114
	v_mul_f32_e32 v118, v119, v118
	v_mul_f32_e32 v114, v114, v123
	v_mul_f32_e32 v123, v118, v115
	v_mul_f32_e32 v118, 0xbfb8aa3b, v120
	v_exp_f32_e32 v118, v118
	v_mul_f32_e32 v115, 0xbfb8aa3b, v128
	v_exp_f32_e32 v115, v115
	v_cvt_pk_bf16_f32 v114, v122, v114
	v_add_f32_e32 v118, 1.0, v118
	v_rcp_f32_e32 v118, v118
	v_add_f32_e32 v115, 1.0, v115
	v_rcp_f32_e32 v115, v115
	v_mul_f32_e32 v118, v120, v118
	v_mul_f32_e32 v120, v118, v116
	v_mul_f32_e32 v116, 0xbfb8aa3b, v129
	v_mul_f32_e32 v118, 0xbfb8aa3b, v121
	v_exp_f32_e32 v116, v116
	v_exp_f32_e32 v118, v118
	v_mul_f32_e32 v115, v128, v115
	v_mul_f32_e32 v115, v115, v124
	v_add_f32_e32 v116, 1.0, v116
	v_add_f32_e32 v118, 1.0, v118
	v_rcp_f32_e32 v116, v116
	v_rcp_f32_e32 v118, v118
	v_mul_f32_e32 v116, v129, v116
	v_mul_f32_e32 v118, v121, v118
	v_mul_f32_e32 v116, v116, v125
	v_mul_f32_e32 v117, v118, v117
	v_lshl_add_u64 v[118:119], v[166:167], 0, v[146:147]
	v_cvt_pk_bf16_f32 v115, v115, v116
	v_cvt_pk_bf16_f32 v116, v126, v123
	v_cvt_pk_bf16_f32 v117, v120, v117
	global_store_dwordx4 v[118:119], v[114:117], off
	s_nop 1
	v_mul_f32_e32 v114, 0xbfb8aa3b, v110
	v_exp_f32_e32 v114, v114
	s_nop 0
	v_add_f32_e32 v114, 1.0, v114
	v_rcp_f32_e32 v114, v114
	s_nop 0
	v_mul_f32_e32 v110, v110, v114
	v_mul_f32_e32 v106, v110, v106
	v_mul_f32_e32 v110, 0xbfb8aa3b, v102
	v_exp_f32_e32 v110, v110
	s_nop 0
	v_add_f32_e32 v110, 1.0, v110
	v_rcp_f32_e32 v110, v110
	s_nop 0
	v_mul_f32_e32 v102, v102, v110
	v_mul_f32_e32 v110, v102, v98
	v_mul_f32_e32 v98, 0xbfb8aa3b, v111
	v_mul_f32_e32 v102, 0xbfb8aa3b, v103
	v_exp_f32_e32 v98, v98
	v_exp_f32_e32 v102, v102
	v_add_f32_e32 v98, 1.0, v98
	v_add_f32_e32 v102, 1.0, v102
	v_rcp_f32_e32 v98, v98
	v_rcp_f32_e32 v102, v102
	v_mul_f32_e32 v98, v111, v98
	v_mul_f32_e32 v102, v103, v102
	v_mul_f32_e32 v98, v98, v107
	v_mul_f32_e32 v107, v102, v99
	v_mul_f32_e32 v102, 0xbfb8aa3b, v104
	v_exp_f32_e32 v102, v102
	v_mul_f32_e32 v99, 0xbfb8aa3b, v112
	v_exp_f32_e32 v99, v99
	v_cvt_pk_bf16_f32 v98, v106, v98
	v_add_f32_e32 v102, 1.0, v102
	v_rcp_f32_e32 v102, v102
	v_add_f32_e32 v99, 1.0, v99
	v_rcp_f32_e32 v99, v99
	v_mul_f32_e32 v102, v104, v102
	v_mul_f32_e32 v104, v102, v100
	v_mul_f32_e32 v100, 0xbfb8aa3b, v113
	v_mul_f32_e32 v102, 0xbfb8aa3b, v105
	v_exp_f32_e32 v100, v100
	v_exp_f32_e32 v102, v102
	v_mul_f32_e32 v99, v112, v99
	v_mul_f32_e32 v99, v99, v108
	v_add_f32_e32 v100, 1.0, v100
	v_add_f32_e32 v102, 1.0, v102
	v_rcp_f32_e32 v100, v100
	v_rcp_f32_e32 v102, v102
	v_mul_f32_e32 v100, v113, v100
	v_mul_f32_e32 v102, v105, v102
	v_mul_f32_e32 v100, v100, v109
	v_mul_f32_e32 v101, v102, v101
	v_lshl_add_u64 v[102:103], v[166:167], 0, v[148:149]
	v_cvt_pk_bf16_f32 v99, v99, v100
	v_cvt_pk_bf16_f32 v100, v110, v107
	v_cvt_pk_bf16_f32 v101, v104, v101
	global_store_dwordx4 v[102:103], v[98:101], off
	s_nop 1
	v_mul_f32_e32 v98, 0xbfb8aa3b, v94
	v_exp_f32_e32 v98, v98
	s_nop 0
	v_add_f32_e32 v98, 1.0, v98
	v_rcp_f32_e32 v98, v98
	s_nop 0
	v_mul_f32_e32 v94, v94, v98
	v_mul_f32_e32 v90, v94, v90
	v_mul_f32_e32 v94, 0xbfb8aa3b, v86
	v_exp_f32_e32 v94, v94
	s_nop 0
	v_add_f32_e32 v94, 1.0, v94
	v_rcp_f32_e32 v94, v94
	s_nop 0
	v_mul_f32_e32 v86, v86, v94
	v_mul_f32_e32 v94, v86, v82
	v_mul_f32_e32 v82, 0xbfb8aa3b, v95
	v_mul_f32_e32 v86, 0xbfb8aa3b, v87
	v_exp_f32_e32 v82, v82
	v_exp_f32_e32 v86, v86
	v_add_f32_e32 v82, 1.0, v82
	v_add_f32_e32 v86, 1.0, v86
	v_rcp_f32_e32 v82, v82
	v_rcp_f32_e32 v86, v86
	v_mul_f32_e32 v82, v95, v82
	v_mul_f32_e32 v86, v87, v86
	v_mul_f32_e32 v82, v82, v91
	v_mul_f32_e32 v91, v86, v83
	v_mul_f32_e32 v86, 0xbfb8aa3b, v88
	v_exp_f32_e32 v86, v86
	v_mul_f32_e32 v83, 0xbfb8aa3b, v96
	v_exp_f32_e32 v83, v83
	v_cvt_pk_bf16_f32 v82, v90, v82
	v_add_f32_e32 v86, 1.0, v86
	v_rcp_f32_e32 v86, v86
	v_add_f32_e32 v83, 1.0, v83
	v_rcp_f32_e32 v83, v83
	v_mul_f32_e32 v86, v88, v86
	v_mul_f32_e32 v88, v86, v84
	v_mul_f32_e32 v84, 0xbfb8aa3b, v97
	v_mul_f32_e32 v86, 0xbfb8aa3b, v89
	v_exp_f32_e32 v84, v84
	v_exp_f32_e32 v86, v86
	v_mul_f32_e32 v83, v96, v83
	v_mul_f32_e32 v83, v83, v92
	v_add_f32_e32 v84, 1.0, v84
	v_add_f32_e32 v86, 1.0, v86
	v_rcp_f32_e32 v84, v84
	v_rcp_f32_e32 v86, v86
	v_mul_f32_e32 v84, v97, v84
	v_mul_f32_e32 v86, v89, v86
	v_mul_f32_e32 v84, v84, v93
	v_mul_f32_e32 v85, v86, v85
	v_lshl_add_u64 v[86:87], v[166:167], 0, v[150:151]
	v_cvt_pk_bf16_f32 v83, v83, v84
	v_cvt_pk_bf16_f32 v84, v94, v91
	v_cvt_pk_bf16_f32 v85, v88, v85
	global_store_dwordx4 v[86:87], v[82:85], off
	s_nop 1
	v_mul_f32_e32 v82, 0xbfb8aa3b, v78
	v_exp_f32_e32 v82, v82
	s_nop 0
	v_add_f32_e32 v82, 1.0, v82
	v_rcp_f32_e32 v82, v82
	s_nop 0
	v_mul_f32_e32 v78, v78, v82
	v_mul_f32_e32 v74, v78, v74
	v_mul_f32_e32 v78, 0xbfb8aa3b, v70
	v_exp_f32_e32 v78, v78
	s_nop 0
	v_add_f32_e32 v78, 1.0, v78
	v_rcp_f32_e32 v78, v78
	s_nop 0
	v_mul_f32_e32 v70, v70, v78
	v_mul_f32_e32 v78, v70, v66
	v_mul_f32_e32 v66, 0xbfb8aa3b, v79
	v_mul_f32_e32 v70, 0xbfb8aa3b, v71
	v_exp_f32_e32 v66, v66
	v_exp_f32_e32 v70, v70
	v_add_f32_e32 v66, 1.0, v66
	v_add_f32_e32 v70, 1.0, v70
	v_rcp_f32_e32 v66, v66
	v_rcp_f32_e32 v70, v70
	v_mul_f32_e32 v66, v79, v66
	v_mul_f32_e32 v70, v71, v70
	v_mul_f32_e32 v66, v66, v75
	v_mul_f32_e32 v75, v70, v67
	v_mul_f32_e32 v70, 0xbfb8aa3b, v72
	v_exp_f32_e32 v70, v70
	v_mul_f32_e32 v67, 0xbfb8aa3b, v80
	v_exp_f32_e32 v67, v67
	v_cvt_pk_bf16_f32 v66, v74, v66
	v_add_f32_e32 v70, 1.0, v70
	v_rcp_f32_e32 v70, v70
	v_add_f32_e32 v67, 1.0, v67
	v_rcp_f32_e32 v67, v67
	v_mul_f32_e32 v70, v72, v70
	v_mul_f32_e32 v72, v70, v68
	v_mul_f32_e32 v68, 0xbfb8aa3b, v81
	v_mul_f32_e32 v70, 0xbfb8aa3b, v73
	v_exp_f32_e32 v68, v68
	v_exp_f32_e32 v70, v70
	v_mul_f32_e32 v67, v80, v67
	v_mul_f32_e32 v67, v67, v76
	v_add_f32_e32 v68, 1.0, v68
	v_add_f32_e32 v70, 1.0, v70
	v_rcp_f32_e32 v68, v68
	v_rcp_f32_e32 v70, v70
	v_mul_f32_e32 v68, v81, v68
	v_mul_f32_e32 v70, v73, v70
	v_mul_f32_e32 v68, v68, v77
	v_mul_f32_e32 v69, v70, v69
	v_lshl_add_u64 v[70:71], v[166:167], 0, v[152:153]
	v_cvt_pk_bf16_f32 v67, v67, v68
	v_cvt_pk_bf16_f32 v68, v78, v75
	v_cvt_pk_bf16_f32 v69, v72, v69
	global_store_dwordx4 v[70:71], v[66:69], off
	s_nop 1
	v_mul_f32_e32 v66, 0xbfb8aa3b, v62
	v_exp_f32_e32 v66, v66
	s_nop 0
	v_add_f32_e32 v66, 1.0, v66
	v_rcp_f32_e32 v66, v66
	s_nop 0
	v_mul_f32_e32 v62, v62, v66
	v_mul_f32_e32 v58, v62, v58
	v_mul_f32_e32 v62, 0xbfb8aa3b, v54
	v_exp_f32_e32 v62, v62
	s_nop 0
	v_add_f32_e32 v62, 1.0, v62
	v_rcp_f32_e32 v62, v62
	s_nop 0
	v_mul_f32_e32 v54, v54, v62
	v_mul_f32_e32 v62, v54, v50
	v_mul_f32_e32 v50, 0xbfb8aa3b, v63
	v_mul_f32_e32 v54, 0xbfb8aa3b, v55
	v_exp_f32_e32 v50, v50
	v_exp_f32_e32 v54, v54
	v_add_f32_e32 v50, 1.0, v50
	v_add_f32_e32 v54, 1.0, v54
	v_rcp_f32_e32 v50, v50
	v_rcp_f32_e32 v54, v54
	v_mul_f32_e32 v50, v63, v50
	v_mul_f32_e32 v54, v55, v54
	v_mul_f32_e32 v50, v50, v59
	v_mul_f32_e32 v59, v54, v51
	v_mul_f32_e32 v54, 0xbfb8aa3b, v56
	v_exp_f32_e32 v54, v54
	v_mul_f32_e32 v51, 0xbfb8aa3b, v64
	v_exp_f32_e32 v51, v51
	v_cvt_pk_bf16_f32 v50, v58, v50
	v_add_f32_e32 v54, 1.0, v54
	v_rcp_f32_e32 v54, v54
	v_add_f32_e32 v51, 1.0, v51
	v_rcp_f32_e32 v51, v51
	v_mul_f32_e32 v54, v56, v54
	v_mul_f32_e32 v56, v54, v52
	v_mul_f32_e32 v52, 0xbfb8aa3b, v65
	v_mul_f32_e32 v54, 0xbfb8aa3b, v57
	v_exp_f32_e32 v52, v52
	v_exp_f32_e32 v54, v54
	v_mul_f32_e32 v51, v64, v51
	v_mul_f32_e32 v51, v51, v60
	v_add_f32_e32 v52, 1.0, v52
	v_add_f32_e32 v54, 1.0, v54
	v_rcp_f32_e32 v52, v52
	v_rcp_f32_e32 v54, v54
	v_mul_f32_e32 v52, v65, v52
	v_mul_f32_e32 v54, v57, v54
	v_mul_f32_e32 v52, v52, v61
	v_mul_f32_e32 v53, v54, v53
	v_lshl_add_u64 v[54:55], v[166:167], 0, v[154:155]
	v_cvt_pk_bf16_f32 v51, v51, v52
	v_cvt_pk_bf16_f32 v52, v62, v59
	v_cvt_pk_bf16_f32 v53, v56, v53
	global_store_dwordx4 v[54:55], v[50:53], off
	s_nop 1
	v_mul_f32_e32 v50, 0xbfb8aa3b, v46
	v_exp_f32_e32 v50, v50
	s_nop 0
	v_add_f32_e32 v50, 1.0, v50
	v_rcp_f32_e32 v50, v50
	s_nop 0
	v_mul_f32_e32 v46, v46, v50
	v_mul_f32_e32 v42, v46, v42
	v_mul_f32_e32 v46, 0xbfb8aa3b, v38
	v_exp_f32_e32 v46, v46
	s_nop 0
	v_add_f32_e32 v46, 1.0, v46
	v_rcp_f32_e32 v46, v46
	s_nop 0
	v_mul_f32_e32 v38, v38, v46
	v_mul_f32_e32 v46, v38, v34
	v_mul_f32_e32 v34, 0xbfb8aa3b, v47
	v_mul_f32_e32 v38, 0xbfb8aa3b, v39
	v_exp_f32_e32 v34, v34
	v_exp_f32_e32 v38, v38
	v_add_f32_e32 v34, 1.0, v34
	v_add_f32_e32 v38, 1.0, v38
	v_rcp_f32_e32 v34, v34
	v_rcp_f32_e32 v38, v38
	v_mul_f32_e32 v34, v47, v34
	v_mul_f32_e32 v38, v39, v38
	v_mul_f32_e32 v34, v34, v43
	v_mul_f32_e32 v43, v38, v35
	v_mul_f32_e32 v38, 0xbfb8aa3b, v40
	v_exp_f32_e32 v38, v38
	v_mul_f32_e32 v35, 0xbfb8aa3b, v48
	v_exp_f32_e32 v35, v35
	v_cvt_pk_bf16_f32 v34, v42, v34
	v_add_f32_e32 v38, 1.0, v38
	v_rcp_f32_e32 v38, v38
	v_add_f32_e32 v35, 1.0, v35
	v_rcp_f32_e32 v35, v35
	v_mul_f32_e32 v38, v40, v38
	v_mul_f32_e32 v40, v38, v36
	v_mul_f32_e32 v36, 0xbfb8aa3b, v49
	v_mul_f32_e32 v38, 0xbfb8aa3b, v41
	v_exp_f32_e32 v36, v36
	v_exp_f32_e32 v38, v38
	v_mul_f32_e32 v35, v48, v35
	v_mul_f32_e32 v35, v35, v44
	v_add_f32_e32 v36, 1.0, v36
	v_add_f32_e32 v38, 1.0, v38
	v_rcp_f32_e32 v36, v36
	v_rcp_f32_e32 v38, v38
	v_mul_f32_e32 v36, v49, v36
	v_mul_f32_e32 v38, v41, v38
	v_mul_f32_e32 v36, v36, v45
	v_mul_f32_e32 v37, v38, v37
	v_lshl_add_u64 v[38:39], v[166:167], 0, v[156:157]
	v_cvt_pk_bf16_f32 v35, v35, v36
	v_cvt_pk_bf16_f32 v36, v46, v43
	v_cvt_pk_bf16_f32 v37, v40, v37
	global_store_dwordx4 v[38:39], v[34:37], off
	s_nop 1
	v_mul_f32_e32 v34, 0xbfb8aa3b, v30
	v_exp_f32_e32 v34, v34
	s_nop 0
	v_add_f32_e32 v34, 1.0, v34
	v_rcp_f32_e32 v34, v34
	s_nop 0
	v_mul_f32_e32 v30, v30, v34
	v_mul_f32_e32 v26, v30, v26
	v_mul_f32_e32 v30, 0xbfb8aa3b, v22
	v_exp_f32_e32 v30, v30
	s_nop 0
	v_add_f32_e32 v30, 1.0, v30
	v_rcp_f32_e32 v30, v30
	s_nop 0
	v_mul_f32_e32 v22, v22, v30
	v_mul_f32_e32 v30, v22, v18
	v_mul_f32_e32 v18, 0xbfb8aa3b, v31
	v_mul_f32_e32 v22, 0xbfb8aa3b, v23
	v_exp_f32_e32 v18, v18
	v_exp_f32_e32 v22, v22
	v_add_f32_e32 v18, 1.0, v18
	v_add_f32_e32 v22, 1.0, v22
	v_rcp_f32_e32 v18, v18
	v_rcp_f32_e32 v22, v22
	v_mul_f32_e32 v18, v31, v18
	v_mul_f32_e32 v22, v23, v22
	v_mul_f32_e32 v18, v18, v27
	v_mul_f32_e32 v27, v22, v19
	v_mul_f32_e32 v22, 0xbfb8aa3b, v24
	v_exp_f32_e32 v22, v22
	v_mul_f32_e32 v19, 0xbfb8aa3b, v32
	v_exp_f32_e32 v19, v19
	v_cvt_pk_bf16_f32 v18, v26, v18
	v_add_f32_e32 v22, 1.0, v22
	v_rcp_f32_e32 v22, v22
	v_add_f32_e32 v19, 1.0, v19
	v_rcp_f32_e32 v19, v19
	v_mul_f32_e32 v22, v24, v22
	v_mul_f32_e32 v24, v22, v20
	v_mul_f32_e32 v20, 0xbfb8aa3b, v33
	v_mul_f32_e32 v22, 0xbfb8aa3b, v25
	v_exp_f32_e32 v20, v20
	v_exp_f32_e32 v22, v22
	v_mul_f32_e32 v19, v32, v19
	v_mul_f32_e32 v19, v19, v28
	v_add_f32_e32 v20, 1.0, v20
	v_add_f32_e32 v22, 1.0, v22
	v_rcp_f32_e32 v20, v20
	v_rcp_f32_e32 v22, v22
	v_mul_f32_e32 v20, v33, v20
	v_mul_f32_e32 v22, v25, v22
	v_mul_f32_e32 v20, v20, v29
	v_mul_f32_e32 v21, v22, v21
	v_lshl_add_u64 v[22:23], v[166:167], 0, v[158:159]
	v_cvt_pk_bf16_f32 v19, v19, v20
	v_cvt_pk_bf16_f32 v20, v30, v27
	v_cvt_pk_bf16_f32 v21, v24, v21
	global_store_dwordx4 v[22:23], v[18:21], off
	s_nop 1
	v_mul_f32_e32 v18, 0xbfb8aa3b, v14
	v_exp_f32_e32 v18, v18
	s_nop 0
	v_add_f32_e32 v18, 1.0, v18
	v_rcp_f32_e32 v18, v18
	s_nop 0
	v_mul_f32_e32 v14, v14, v18
	v_mul_f32_e32 v10, v14, v10
	v_mul_f32_e32 v14, 0xbfb8aa3b, v6
	v_exp_f32_e32 v14, v14
	s_nop 0
	v_add_f32_e32 v14, 1.0, v14
	v_rcp_f32_e32 v14, v14
	s_nop 0
	v_mul_f32_e32 v6, v6, v14
	v_mul_f32_e32 v14, v6, v2
	v_mul_f32_e32 v2, 0xbfb8aa3b, v15
	v_mul_f32_e32 v6, 0xbfb8aa3b, v7
	v_exp_f32_e32 v2, v2
	v_exp_f32_e32 v6, v6
	v_add_f32_e32 v2, 1.0, v2
	v_add_f32_e32 v6, 1.0, v6
	v_rcp_f32_e32 v2, v2
	v_rcp_f32_e32 v6, v6
	v_mul_f32_e32 v2, v15, v2
	v_mul_f32_e32 v6, v7, v6
	v_mul_f32_e32 v2, v2, v11
	v_mul_f32_e32 v11, v6, v3
	v_mul_f32_e32 v6, 0xbfb8aa3b, v8
	v_exp_f32_e32 v6, v6
	v_mul_f32_e32 v3, 0xbfb8aa3b, v16
	v_exp_f32_e32 v3, v3
	v_cvt_pk_bf16_f32 v2, v10, v2
	v_add_f32_e32 v6, 1.0, v6
	v_rcp_f32_e32 v6, v6
	v_add_f32_e32 v3, 1.0, v3
	v_rcp_f32_e32 v3, v3
	v_mul_f32_e32 v6, v8, v6
	v_mul_f32_e32 v8, v6, v4
	v_mul_f32_e32 v4, 0xbfb8aa3b, v17
	v_mul_f32_e32 v6, 0xbfb8aa3b, v9
	v_exp_f32_e32 v4, v4
	v_exp_f32_e32 v6, v6
	v_mul_f32_e32 v3, v16, v3
	v_mul_f32_e32 v3, v3, v12
	v_add_f32_e32 v4, 1.0, v4
	v_add_f32_e32 v6, 1.0, v6
	v_rcp_f32_e32 v4, v4
	v_rcp_f32_e32 v6, v6
	v_mul_f32_e32 v4, v17, v4
	v_mul_f32_e32 v6, v9, v6
	v_mul_f32_e32 v4, v4, v13
	v_mul_f32_e32 v5, v6, v5
	v_lshl_add_u64 v[6:7], v[166:167], 0, v[160:161]
	v_cvt_pk_bf16_f32 v3, v3, v4
	v_cvt_pk_bf16_f32 v4, v14, v11
	v_cvt_pk_bf16_f32 v5, v8, v5
	global_store_dwordx4 v[6:7], v[2:5], off
	s_cbranch_vccz .LBB0_105
	s_waitcnt vmcnt(0)
	v_readlane_b32 s50, v254, 28
	v_readlane_b32 s56, v254, 30
	v_readlane_b32 s60, v254, 39
	s_cmpk_gt_u32 s4, 0xff
	v_readlane_b32 s51, v254, 29
	v_readlane_b32 s57, v254, 31
	v_readlane_b32 s61, v254, 40
	s_mov_b64 s[58:59], s[84:85]
	s_cbranch_scc1 .LBB0_112
	s_barrier

.LBB0_182:
	s_add_u32 s26, s38, 0x4000
	s_addc_u32 s27, s39, 0
	s_cmpk_eq_i32 s61, 0x54
	s_cselect_b32 s48, s0, s26
	s_cselect_b32 s49, s1, s27
	s_cselect_b32 s26, s24, s59
	s_cselect_b32 s27, s25, s60
	s_add_u32 s42, s48, 0x8000
	s_addc_u32 s43, s49, 0
	s_add_i32 s62, 0, 0x10000
	v_add_u32_e32 v134, s62, v155
	ds_read_b128 v[148:151], v134
	ds_read_b128 v[158:161], v134 offset:1024
	ds_read_b128 v[162:165], v134 offset:2048
	ds_read_b128 v[180:183], v134 offset:3072
	s_add_i32 m0, s7, 0xc000
	ds_read_b128 v[184:187], v157
	ds_read_b128 v[188:191], v157 offset:1024
	ds_read_b128 v[192:195], v157 offset:2048
	ds_read_b128 v[196:199], v157 offset:3072
	ds_read_b128 v[200:203], v157 offset:4096
	ds_read_b128 v[204:207], v157 offset:5120
	ds_read_b128 v[208:211], v157 offset:6144
	ds_read_b128 v[212:215], v157 offset:7168
	global_load_lds_dwordx4 v144, s[38:39]
	s_add_i32 m0, s7, 0xe000
	s_nop 0
	global_load_lds_dwordx4 v146, s[38:39]
	s_waitcnt lgkmcnt(8)
	s_barrier
	s_waitcnt lgkmcnt(0)
	s_setprio 1
	s_waitcnt lgkmcnt(0)
	v_mfma_f32_16x16x32_bf16 v[126:129], v[148:151], v[184:187], v[126:129]
	v_mfma_f32_16x16x32_bf16 v[122:125], v[162:165], v[184:187], v[122:125]
	v_mfma_f32_16x16x32_bf16 v[110:113], v[148:151], v[192:195], v[110:113]
	v_mfma_f32_16x16x32_bf16 v[106:109], v[162:165], v[192:195], v[106:109]
	v_mfma_f32_16x16x32_bf16 v[94:97], v[148:151], v[200:203], v[94:97]
	v_mfma_f32_16x16x32_bf16 v[90:93], v[162:165], v[200:203], v[90:93]
	v_mfma_f32_16x16x32_bf16 v[78:81], v[148:151], v[208:211], v[78:81]
	v_mfma_f32_16x16x32_bf16 v[74:77], v[162:165], v[208:211], v[74:77]
	v_mfma_f32_16x16x32_bf16 v[126:129], v[158:161], v[188:191], v[126:129]
	v_mfma_f32_16x16x32_bf16 v[122:125], v[180:183], v[188:191], v[122:125]
	v_mfma_f32_16x16x32_bf16 v[110:113], v[158:161], v[196:199], v[110:113]
	v_mfma_f32_16x16x32_bf16 v[106:109], v[180:183], v[196:199], v[106:109]
	v_mfma_f32_16x16x32_bf16 v[94:97], v[158:161], v[204:207], v[94:97]
	v_mfma_f32_16x16x32_bf16 v[90:93], v[180:183], v[204:207], v[90:93]
	v_mfma_f32_16x16x32_bf16 v[78:81], v[158:161], v[212:215], v[78:81]
	v_mfma_f32_16x16x32_bf16 v[74:77], v[180:183], v[212:215], v[74:77]
	s_setprio 0
	s_barrier
	s_add_i32 s64, 0, 0x14000
	s_add_i32 s62, s62, s6
	ds_read_b128 v[216:219], v134 offset:16384
	ds_read_b128 v[220:223], v134 offset:17408
	ds_read_b128 v[224:227], v134 offset:18432
	ds_read_b128 v[228:231], v134 offset:19456
	s_mov_b32 m0, s62
	global_load_lds_dwordx4 v0, s[26:27]
	s_add_i32 m0, s62, 0x2000
	s_nop 0
	global_load_lds_dwordx4 v138, s[26:27]
	s_barrier
	s_waitcnt lgkmcnt(0)
	s_setprio 1
	s_waitcnt lgkmcnt(0)
	v_mfma_f32_16x16x32_bf16 v[118:121], v[216:219], v[184:187], v[118:121]
	v_mfma_f32_16x16x32_bf16 v[114:117], v[224:227], v[184:187], v[114:117]
	v_mfma_f32_16x16x32_bf16 v[102:105], v[216:219], v[192:195], v[102:105]
	v_mfma_f32_16x16x32_bf16 v[98:101], v[224:227], v[192:195], v[98:101]
	v_mfma_f32_16x16x32_bf16 v[86:89], v[216:219], v[200:203], v[86:89]
	v_mfma_f32_16x16x32_bf16 v[82:85], v[224:227], v[200:203], v[82:85]
	v_mfma_f32_16x16x32_bf16 v[70:73], v[216:219], v[208:211], v[70:73]
	v_mfma_f32_16x16x32_bf16 v[66:69], v[224:227], v[208:211], v[66:69]
	v_mfma_f32_16x16x32_bf16 v[118:121], v[220:223], v[188:191], v[118:121]
	v_mfma_f32_16x16x32_bf16 v[114:117], v[228:231], v[188:191], v[114:117]
	v_mfma_f32_16x16x32_bf16 v[102:105], v[220:223], v[196:199], v[102:105]
	v_mfma_f32_16x16x32_bf16 v[98:101], v[228:231], v[196:199], v[98:101]
	v_mfma_f32_16x16x32_bf16 v[86:89], v[220:223], v[204:207], v[86:89]
	v_mfma_f32_16x16x32_bf16 v[82:85], v[228:231], v[204:207], v[82:85]
	v_mfma_f32_16x16x32_bf16 v[70:73], v[220:223], v[212:215], v[70:73]
	v_mfma_f32_16x16x32_bf16 v[66:69], v[228:231], v[212:215], v[66:69]
	s_setprio 0
	s_mov_b32 m0, s7
	s_barrier
	ds_read_b128 v[184:187], v157 offset:16384
	ds_read_b128 v[188:191], v157 offset:17408
	ds_read_b128 v[192:195], v157 offset:18432
	ds_read_b128 v[196:199], v157 offset:19456
	ds_read_b128 v[200:203], v157 offset:20480
	ds_read_b128 v[204:207], v157 offset:21504
	ds_read_b128 v[208:211], v157 offset:22528
	ds_read_b128 v[212:215], v157 offset:23552
	global_load_lds_dwordx4 v142, s[48:49]
	s_mov_b32 m0, s14
	s_nop 0
	global_load_lds_dwordx4 v140, s[48:49]
	s_barrier
	s_waitcnt lgkmcnt(0)
	s_setprio 1
	s_waitcnt lgkmcnt(0)
	v_mfma_f32_16x16x32_bf16 v[62:65], v[148:151], v[184:187], v[62:65]
	v_mfma_f32_16x16x32_bf16 v[58:61], v[162:165], v[184:187], v[58:61]
	v_mfma_f32_16x16x32_bf16 v[46:49], v[148:151], v[192:195], v[46:49]
	v_mfma_f32_16x16x32_bf16 v[42:45], v[162:165], v[192:195], v[42:45]
	v_mfma_f32_16x16x32_bf16 v[30:33], v[148:151], v[200:203], v[30:33]
	v_mfma_f32_16x16x32_bf16 v[26:29], v[162:165], v[200:203], v[26:29]
	v_mfma_f32_16x16x32_bf16 v[14:17], v[148:151], v[208:211], v[14:17]
	v_mfma_f32_16x16x32_bf16 v[10:13], v[162:165], v[208:211], v[10:13]
	v_mfma_f32_16x16x32_bf16 v[62:65], v[158:161], v[188:191], v[62:65]
	v_mfma_f32_16x16x32_bf16 v[58:61], v[180:183], v[188:191], v[58:61]
	v_mfma_f32_16x16x32_bf16 v[46:49], v[158:161], v[196:199], v[46:49]
	v_mfma_f32_16x16x32_bf16 v[42:45], v[180:183], v[196:199], v[42:45]
	v_mfma_f32_16x16x32_bf16 v[30:33], v[158:161], v[204:207], v[30:33]
	v_mfma_f32_16x16x32_bf16 v[26:29], v[180:183], v[204:207], v[26:29]
	v_mfma_f32_16x16x32_bf16 v[14:17], v[158:161], v[212:215], v[14:17]
	v_mfma_f32_16x16x32_bf16 v[10:13], v[180:183], v[212:215], v[10:13]
	s_setprio 0
	s_barrier
	s_add_u32 s62, s26, 0x160000
	s_addc_u32 s63, s27, 0
	s_add_i32 s64, s64, s6
	s_mov_b32 m0, s64
	s_nop 0
	global_load_lds_dwordx4 v0, s[62:63]
	s_add_i32 m0, s64, 0x2000
	s_nop 0
	global_load_lds_dwordx4 v138, s[62:63]
	s_waitcnt vmcnt(6)
	s_barrier
	s_setprio 1
	v_mfma_f32_16x16x32_bf16 v[54:57], v[216:219], v[184:187], v[54:57]
	v_mfma_f32_16x16x32_bf16 v[50:53], v[224:227], v[184:187], v[50:53]
	v_mfma_f32_16x16x32_bf16 v[38:41], v[216:219], v[192:195], v[38:41]
	v_mfma_f32_16x16x32_bf16 v[34:37], v[224:227], v[192:195], v[34:37]
	v_mfma_f32_16x16x32_bf16 v[22:25], v[216:219], v[200:203], v[22:25]
	v_mfma_f32_16x16x32_bf16 v[18:21], v[224:227], v[200:203], v[18:21]
	v_mfma_f32_16x16x32_bf16 v[6:9], v[216:219], v[208:211], v[6:9]
	v_mfma_f32_16x16x32_bf16 v[2:5], v[224:227], v[208:211], v[2:5]
	v_mfma_f32_16x16x32_bf16 v[54:57], v[220:223], v[188:191], v[54:57]
	v_mfma_f32_16x16x32_bf16 v[50:53], v[228:231], v[188:191], v[50:53]
	v_mfma_f32_16x16x32_bf16 v[38:41], v[220:223], v[196:199], v[38:41]
	v_mfma_f32_16x16x32_bf16 v[34:37], v[228:231], v[196:199], v[34:37]
	v_mfma_f32_16x16x32_bf16 v[22:25], v[220:223], v[204:207], v[22:25]
	v_mfma_f32_16x16x32_bf16 v[18:21], v[228:231], v[204:207], v[18:21]
	v_mfma_f32_16x16x32_bf16 v[6:9], v[220:223], v[212:215], v[6:9]
	v_mfma_f32_16x16x32_bf16 v[2:5], v[228:231], v[212:215], v[2:5]
	s_setprio 0
	s_add_i32 s62, 0, 0x18000
	s_barrier
	ds_read_b128 v[148:151], v134 offset:32768
	ds_read_b128 v[158:161], v134 offset:33792
	ds_read_b128 v[162:165], v134 offset:34816
	ds_read_b128 v[180:183], v134 offset:35840
	s_add_u32 s48, s48, 0x4000
	s_addc_u32 s49, s49, 0
	s_mov_b32 m0, s50
	ds_read_b128 v[184:187], v157 offset:32768
	ds_read_b128 v[188:191], v157 offset:33792
	ds_read_b128 v[192:195], v157 offset:34816
	ds_read_b128 v[196:199], v157 offset:35840
	ds_read_b128 v[200:203], v157 offset:36864
	ds_read_b128 v[204:207], v157 offset:37888
	ds_read_b128 v[208:211], v157 offset:38912
	ds_read_b128 v[212:215], v157 offset:39936
	global_load_lds_dwordx4 v142, s[48:49]
	s_mov_b32 m0, s51
	s_nop 0
	global_load_lds_dwordx4 v140, s[48:49]
	s_waitcnt lgkmcnt(8)
	s_barrier
	s_waitcnt lgkmcnt(0)
	s_setprio 1
	s_waitcnt lgkmcnt(0)
	v_mfma_f32_16x16x32_bf16 v[126:129], v[148:151], v[184:187], v[126:129]
	v_mfma_f32_16x16x32_bf16 v[122:125], v[162:165], v[184:187], v[122:125]
	v_mfma_f32_16x16x32_bf16 v[110:113], v[148:151], v[192:195], v[110:113]
	v_mfma_f32_16x16x32_bf16 v[106:109], v[162:165], v[192:195], v[106:109]
	v_mfma_f32_16x16x32_bf16 v[94:97], v[148:151], v[200:203], v[94:97]
	v_mfma_f32_16x16x32_bf16 v[90:93], v[162:165], v[200:203], v[90:93]
	v_mfma_f32_16x16x32_bf16 v[78:81], v[148:151], v[208:211], v[78:81]
	v_mfma_f32_16x16x32_bf16 v[74:77], v[162:165], v[208:211], v[74:77]
	v_mfma_f32_16x16x32_bf16 v[126:129], v[158:161], v[188:191], v[126:129]
	v_mfma_f32_16x16x32_bf16 v[122:125], v[180:183], v[188:191], v[122:125]
	v_mfma_f32_16x16x32_bf16 v[110:113], v[158:161], v[196:199], v[110:113]
	v_mfma_f32_16x16x32_bf16 v[106:109], v[180:183], v[196:199], v[106:109]
	v_mfma_f32_16x16x32_bf16 v[94:97], v[158:161], v[204:207], v[94:97]
	v_mfma_f32_16x16x32_bf16 v[90:93], v[180:183], v[204:207], v[90:93]
	v_mfma_f32_16x16x32_bf16 v[78:81], v[158:161], v[212:215], v[78:81]
	v_mfma_f32_16x16x32_bf16 v[74:77], v[180:183], v[212:215], v[74:77]
	s_setprio 0
	s_barrier
	s_add_i32 s48, 0, 0x1c000
	s_add_i32 s49, s62, s6
	s_add_u32 s100, s26, s10
	s_addc_u32 s101, s27, s11
	s_mov_b32 m0, s49
	ds_read_b128 v[216:219], v134 offset:49152
	ds_read_b128 v[220:223], v134 offset:50176
	ds_read_b128 v[224:227], v134 offset:51200
	ds_read_b128 v[228:231], v134 offset:52224
	global_load_lds_dwordx4 v0, s[100:101]
	s_add_u32 s100, s26, s10
	s_addc_u32 s101, s27, s11
	s_add_i32 m0, s49, 0x2000
	s_nop 0
	global_load_lds_dwordx4 v138, s[100:101]
	s_barrier
	s_waitcnt lgkmcnt(0)
	s_setprio 1
	s_waitcnt lgkmcnt(0)
	v_mfma_f32_16x16x32_bf16 v[118:121], v[216:219], v[184:187], v[118:121]
	v_mfma_f32_16x16x32_bf16 v[114:117], v[224:227], v[184:187], v[114:117]
	v_mfma_f32_16x16x32_bf16 v[102:105], v[216:219], v[192:195], v[102:105]
	v_mfma_f32_16x16x32_bf16 v[98:101], v[224:227], v[192:195], v[98:101]
	v_mfma_f32_16x16x32_bf16 v[86:89], v[216:219], v[200:203], v[86:89]
	v_mfma_f32_16x16x32_bf16 v[82:85], v[224:227], v[200:203], v[82:85]
	v_mfma_f32_16x16x32_bf16 v[70:73], v[216:219], v[208:211], v[70:73]
	v_mfma_f32_16x16x32_bf16 v[66:69], v[224:227], v[208:211], v[66:69]
	v_mfma_f32_16x16x32_bf16 v[118:121], v[220:223], v[188:191], v[118:121]
	v_mfma_f32_16x16x32_bf16 v[114:117], v[228:231], v[188:191], v[114:117]
	v_mfma_f32_16x16x32_bf16 v[102:105], v[220:223], v[196:199], v[102:105]
	v_mfma_f32_16x16x32_bf16 v[98:101], v[228:231], v[196:199], v[98:101]
	v_mfma_f32_16x16x32_bf16 v[86:89], v[220:223], v[204:207], v[86:89]
	v_mfma_f32_16x16x32_bf16 v[82:85], v[228:231], v[204:207], v[82:85]
	v_mfma_f32_16x16x32_bf16 v[70:73], v[220:223], v[212:215], v[70:73]
	v_mfma_f32_16x16x32_bf16 v[66:69], v[228:231], v[212:215], v[66:69]
	s_setprio 0
	s_mov_b32 m0, s52
	s_barrier
	ds_read_b128 v[184:187], v157 offset:49152
	ds_read_b128 v[188:191], v157 offset:50176
	ds_read_b128 v[192:195], v157 offset:51200
	ds_read_b128 v[196:199], v157 offset:52224
	ds_read_b128 v[200:203], v157 offset:53248
	ds_read_b128 v[204:207], v157 offset:54272
	ds_read_b128 v[208:211], v157 offset:55296
	ds_read_b128 v[212:215], v157 offset:56320
	global_load_lds_dwordx4 v142, s[42:43]
	s_mov_b32 m0, s53
	s_nop 0
	global_load_lds_dwordx4 v140, s[42:43]
	s_barrier
	s_waitcnt lgkmcnt(0)
	s_setprio 1
	s_waitcnt lgkmcnt(0)
	v_mfma_f32_16x16x32_bf16 v[62:65], v[148:151], v[184:187], v[62:65]
	v_mfma_f32_16x16x32_bf16 v[58:61], v[162:165], v[184:187], v[58:61]
	v_mfma_f32_16x16x32_bf16 v[46:49], v[148:151], v[192:195], v[46:49]
	v_mfma_f32_16x16x32_bf16 v[42:45], v[162:165], v[192:195], v[42:45]
	v_mfma_f32_16x16x32_bf16 v[30:33], v[148:151], v[200:203], v[30:33]
	v_mfma_f32_16x16x32_bf16 v[26:29], v[162:165], v[200:203], v[26:29]
	v_mfma_f32_16x16x32_bf16 v[14:17], v[148:151], v[208:211], v[14:17]
	v_mfma_f32_16x16x32_bf16 v[10:13], v[162:165], v[208:211], v[10:13]
	v_mfma_f32_16x16x32_bf16 v[62:65], v[158:161], v[188:191], v[62:65]
	v_mfma_f32_16x16x32_bf16 v[58:61], v[180:183], v[188:191], v[58:61]
	v_mfma_f32_16x16x32_bf16 v[46:49], v[158:161], v[196:199], v[46:49]
	v_mfma_f32_16x16x32_bf16 v[42:45], v[180:183], v[196:199], v[42:45]
	v_mfma_f32_16x16x32_bf16 v[30:33], v[158:161], v[204:207], v[30:33]
	v_mfma_f32_16x16x32_bf16 v[26:29], v[180:183], v[204:207], v[26:29]
	v_mfma_f32_16x16x32_bf16 v[14:17], v[158:161], v[212:215], v[14:17]
	v_mfma_f32_16x16x32_bf16 v[10:13], v[180:183], v[212:215], v[10:13]
	s_setprio 0
	s_barrier
	s_add_u32 s26, s26, 0x160080
	s_addc_u32 s27, s27, 0
	s_add_i32 s42, s48, s6
	s_mov_b32 m0, s42
	s_nop 0
	global_load_lds_dwordx4 v0, s[26:27]
	s_add_i32 m0, s42, 0x2000
	s_nop 0
	global_load_lds_dwordx4 v138, s[26:27]
	s_waitcnt vmcnt(6)
	s_barrier
	s_setprio 1
	v_mfma_f32_16x16x32_bf16 v[54:57], v[216:219], v[184:187], v[54:57]
	v_mfma_f32_16x16x32_bf16 v[50:53], v[224:227], v[184:187], v[50:53]
	v_mfma_f32_16x16x32_bf16 v[38:41], v[216:219], v[192:195], v[38:41]
	v_mfma_f32_16x16x32_bf16 v[34:37], v[224:227], v[192:195], v[34:37]
	v_mfma_f32_16x16x32_bf16 v[22:25], v[216:219], v[200:203], v[22:25]
	v_mfma_f32_16x16x32_bf16 v[18:21], v[224:227], v[200:203], v[18:21]
	v_mfma_f32_16x16x32_bf16 v[6:9], v[216:219], v[208:211], v[6:9]
	v_mfma_f32_16x16x32_bf16 v[2:5], v[224:227], v[208:211], v[2:5]
	v_mfma_f32_16x16x32_bf16 v[54:57], v[220:223], v[188:191], v[54:57]
	v_mfma_f32_16x16x32_bf16 v[50:53], v[228:231], v[188:191], v[50:53]
	v_mfma_f32_16x16x32_bf16 v[38:41], v[220:223], v[196:199], v[38:41]
	v_mfma_f32_16x16x32_bf16 v[34:37], v[228:231], v[196:199], v[34:37]
	v_mfma_f32_16x16x32_bf16 v[22:25], v[220:223], v[204:207], v[22:25]
	v_mfma_f32_16x16x32_bf16 v[18:21], v[228:231], v[204:207], v[18:21]
	v_mfma_f32_16x16x32_bf16 v[6:9], v[220:223], v[212:215], v[6:9]
	v_mfma_f32_16x16x32_bf16 v[2:5], v[228:231], v[212:215], v[2:5]
	s_setprio 0
	s_add_i32 s61, s61, 2
	s_add_u32 s59, s59, 0x100
	s_addc_u32 s60, s60, 0
	s_add_u32 s38, s38, 0x10000
	s_addc_u32 s39, s39, 0
	s_cmpk_gt_u32 s61, 0x55
	s_barrier
	s_cbranch_scc0 .LBB0_182
	v_lshl_add_u32 v152, s58, 8, v154
	v_lshl_or_b32 v150, s57, 8, v156
	v_ashrrev_i32_e32 v153, 31, v152
	v_ashrrev_i32_e32 v151, 31, v150
	v_lshlrev_b64 v[134:135], 11, v[152:153]
	v_lshl_add_u64 v[134:135], v[134:135], 0, v[150:151]
	v_lshlrev_b64 v[148:149], 2, v[134:135]
	v_lshl_add_u64 v[134:135], s[22:23], 0, v[148:149]
	v_lshl_add_u64 v[158:159], s[76:77], 0, v[148:149]
	v_readlane_b32 s62, v254, 34
	v_readlane_b32 s64, v254, 36
	v_readlane_b32 s60, v254, 39
	s_and_b64 vcc, exec, s[40:41]
	s_mov_b32 s57, s55
	s_mov_b32 s58, s56
	s_mov_b64 s[38:39], s[0:1]
	v_readlane_b32 s63, v254, 35
	v_readlane_b32 s65, v254, 37
	v_readlane_b32 s61, v254, 40
	v_mov_b64_e32 v[162:163], v[134:135]
	v_mov_b64_e32 v[152:153], v[158:159]
	global_load_dwordx4 v[180:183], v[162:163], off
	global_load_dwordx4 v[184:187], v[162:163], off offset:16
	global_load_dwordx4 v[188:191], v[162:163], off offset:512
	global_load_dwordx4 v[192:195], v[162:163], off offset:528
	s_mov_b64 s[26:27], 0x20000
	v_lshl_add_u64 v[164:165], v[134:135], 0, s[26:27]
	v_lshl_add_u64 v[160:161], v[158:159], 0, s[26:27]
	global_load_dwordx4 v[196:199], v[164:165], off
	global_load_dwordx4 v[200:203], v[164:165], off offset:16
	global_load_dwordx4 v[204:207], v[164:165], off offset:512
	global_load_dwordx4 v[208:211], v[164:165], off offset:528
	s_mov_b64 s[26:27], 0x40000
	v_lshl_add_u64 v[150:151], v[134:135], 0, s[26:27]
	v_lshl_add_u64 v[148:149], v[158:159], 0, s[26:27]
	global_load_dwordx4 v[212:215], v[150:151], off
	global_load_dwordx4 v[216:219], v[150:151], off offset:16
	global_load_dwordx4 v[220:223], v[150:151], off offset:512
	global_load_dwordx4 v[224:227], v[150:151], off offset:528
	s_waitcnt vmcnt(8)
	v_pk_fma_f32 v[126:127], v[126:127], 0.5, v[180:181] op_sel_hi:[1,0,1]
	v_pk_fma_f32 v[128:129], v[128:129], 0.5, v[182:183] op_sel_hi:[1,0,1]
	v_pk_fma_f32 v[122:123], v[122:123], 0.5, v[184:185] op_sel_hi:[1,0,1]
	v_pk_fma_f32 v[124:125], v[124:125], 0.5, v[186:187] op_sel_hi:[1,0,1]
	v_pk_fma_f32 v[118:119], v[118:119], 0.5, v[188:189] op_sel_hi:[1,0,1]
	v_pk_fma_f32 v[120:121], v[120:121], 0.5, v[190:191] op_sel_hi:[1,0,1]
	v_pk_fma_f32 v[114:115], v[114:115], 0.5, v[192:193] op_sel_hi:[1,0,1]
	v_pk_fma_f32 v[116:117], v[116:117], 0.5, v[194:195] op_sel_hi:[1,0,1]
	global_store_dwordx4 v[152:153], v[126:129], off
	global_store_dwordx4 v[152:153], v[122:125], off offset:16
	global_store_dwordx4 v[152:153], v[118:121], off offset:512
	global_store_dwordx4 v[152:153], v[114:117], off offset:528
	s_mov_b64 s[26:27], 0x60000
	v_lshl_add_u64 v[228:229], v[134:135], 0, s[26:27]
	v_lshl_add_u64 v[230:231], v[158:159], 0, s[26:27]
	global_load_dwordx4 v[180:183], v[228:229], off
	global_load_dwordx4 v[184:187], v[228:229], off offset:16
	global_load_dwordx4 v[188:191], v[228:229], off offset:512
	global_load_dwordx4 v[192:195], v[228:229], off offset:528
	s_waitcnt vmcnt(12)
	v_pk_fma_f32 v[110:111], v[110:111], 0.5, v[196:197] op_sel_hi:[1,0,1]
	v_pk_fma_f32 v[112:113], v[112:113], 0.5, v[198:199] op_sel_hi:[1,0,1]
	v_pk_fma_f32 v[106:107], v[106:107], 0.5, v[200:201] op_sel_hi:[1,0,1]
	v_pk_fma_f32 v[108:109], v[108:109], 0.5, v[202:203] op_sel_hi:[1,0,1]
	v_pk_fma_f32 v[102:103], v[102:103], 0.5, v[204:205] op_sel_hi:[1,0,1]
	v_pk_fma_f32 v[104:105], v[104:105], 0.5, v[206:207] op_sel_hi:[1,0,1]
	v_pk_fma_f32 v[98:99], v[98:99], 0.5, v[208:209] op_sel_hi:[1,0,1]
	v_pk_fma_f32 v[100:101], v[100:101], 0.5, v[210:211] op_sel_hi:[1,0,1]
	global_store_dwordx4 v[160:161], v[110:113], off
	global_store_dwordx4 v[160:161], v[106:109], off offset:16
	global_store_dwordx4 v[160:161], v[102:105], off offset:512
	global_store_dwordx4 v[160:161], v[98:101], off offset:528
	s_mov_b64 s[26:27], 0x100000
	v_lshl_add_u64 v[162:163], v[134:135], 0, s[26:27]
	v_lshl_add_u64 v[152:153], v[158:159], 0, s[26:27]
	global_load_dwordx4 v[196:199], v[162:163], off
	global_load_dwordx4 v[200:203], v[162:163], off offset:16
	global_load_dwordx4 v[204:207], v[162:163], off offset:512
	global_load_dwordx4 v[208:211], v[162:163], off offset:528
	s_waitcnt vmcnt(16)
	v_pk_fma_f32 v[94:95], v[94:95], 0.5, v[212:213] op_sel_hi:[1,0,1]
	v_pk_fma_f32 v[96:97], v[96:97], 0.5, v[214:215] op_sel_hi:[1,0,1]
	v_pk_fma_f32 v[90:91], v[90:91], 0.5, v[216:217] op_sel_hi:[1,0,1]
	v_pk_fma_f32 v[92:93], v[92:93], 0.5, v[218:219] op_sel_hi:[1,0,1]
	v_pk_fma_f32 v[86:87], v[86:87], 0.5, v[220:221] op_sel_hi:[1,0,1]
	v_pk_fma_f32 v[88:89], v[88:89], 0.5, v[222:223] op_sel_hi:[1,0,1]
	v_pk_fma_f32 v[82:83], v[82:83], 0.5, v[224:225] op_sel_hi:[1,0,1]
	v_pk_fma_f32 v[84:85], v[84:85], 0.5, v[226:227] op_sel_hi:[1,0,1]
	global_store_dwordx4 v[148:149], v[94:97], off
	global_store_dwordx4 v[148:149], v[90:93], off offset:16
	global_store_dwordx4 v[148:149], v[86:89], off offset:512
	global_store_dwordx4 v[148:149], v[82:85], off offset:528
	s_mov_b64 s[26:27], 0x120000
	v_lshl_add_u64 v[164:165], v[134:135], 0, s[26:27]
	v_lshl_add_u64 v[160:161], v[158:159], 0, s[26:27]
	global_load_dwordx4 v[212:215], v[164:165], off
	global_load_dwordx4 v[216:219], v[164:165], off offset:16
	global_load_dwordx4 v[220:223], v[164:165], off offset:512
	global_load_dwordx4 v[224:227], v[164:165], off offset:528
	s_waitcnt vmcnt(16)
	v_pk_fma_f32 v[78:79], v[78:79], 0.5, v[180:181] op_sel_hi:[1,0,1]
	v_pk_fma_f32 v[80:81], v[80:81], 0.5, v[182:183] op_sel_hi:[1,0,1]
	v_pk_fma_f32 v[74:75], v[74:75], 0.5, v[184:185] op_sel_hi:[1,0,1]
	v_pk_fma_f32 v[76:77], v[76:77], 0.5, v[186:187] op_sel_hi:[1,0,1]
	v_pk_fma_f32 v[70:71], v[70:71], 0.5, v[188:189] op_sel_hi:[1,0,1]
	v_pk_fma_f32 v[72:73], v[72:73], 0.5, v[190:191] op_sel_hi:[1,0,1]
	v_pk_fma_f32 v[66:67], v[66:67], 0.5, v[192:193] op_sel_hi:[1,0,1]
	v_pk_fma_f32 v[68:69], v[68:69], 0.5, v[194:195] op_sel_hi:[1,0,1]
	global_store_dwordx4 v[230:231], v[78:81], off
	global_store_dwordx4 v[230:231], v[74:77], off offset:16
	global_store_dwordx4 v[230:231], v[70:73], off offset:512
	global_store_dwordx4 v[230:231], v[66:69], off offset:528
	s_mov_b64 s[26:27], 0x140000
	v_lshl_add_u64 v[150:151], v[134:135], 0, s[26:27]
	v_lshl_add_u64 v[148:149], v[158:159], 0, s[26:27]
	global_load_dwordx4 v[180:183], v[150:151], off
	global_load_dwordx4 v[184:187], v[150:151], off offset:16
	global_load_dwordx4 v[188:191], v[150:151], off offset:512
	global_load_dwordx4 v[192:195], v[150:151], off offset:528
	s_waitcnt vmcnt(16)
	v_pk_fma_f32 v[62:63], v[62:63], 0.5, v[196:197] op_sel_hi:[1,0,1]
	v_pk_fma_f32 v[64:65], v[64:65], 0.5, v[198:199] op_sel_hi:[1,0,1]
	v_pk_fma_f32 v[58:59], v[58:59], 0.5, v[200:201] op_sel_hi:[1,0,1]
	v_pk_fma_f32 v[60:61], v[60:61], 0.5, v[202:203] op_sel_hi:[1,0,1]
	v_pk_fma_f32 v[54:55], v[54:55], 0.5, v[204:205] op_sel_hi:[1,0,1]
	v_pk_fma_f32 v[56:57], v[56:57], 0.5, v[206:207] op_sel_hi:[1,0,1]
	v_pk_fma_f32 v[50:51], v[50:51], 0.5, v[208:209] op_sel_hi:[1,0,1]
	v_pk_fma_f32 v[52:53], v[52:53], 0.5, v[210:211] op_sel_hi:[1,0,1]
	global_store_dwordx4 v[152:153], v[62:65], off
	global_store_dwordx4 v[152:153], v[58:61], off offset:16
	global_store_dwordx4 v[152:153], v[54:57], off offset:512
	global_store_dwordx4 v[152:153], v[50:53], off offset:528
	s_mov_b64 s[26:27], 0x160000
	v_lshl_add_u64 v[228:229], v[134:135], 0, s[26:27]
	v_lshl_add_u64 v[230:231], v[158:159], 0, s[26:27]
	global_load_dwordx4 v[196:199], v[228:229], off
	global_load_dwordx4 v[200:203], v[228:229], off offset:16
	global_load_dwordx4 v[204:207], v[228:229], off offset:512
	global_load_dwordx4 v[208:211], v[228:229], off offset:528
	s_waitcnt vmcnt(16)
	v_pk_fma_f32 v[46:47], v[46:47], 0.5, v[212:213] op_sel_hi:[1,0,1]
	v_pk_fma_f32 v[48:49], v[48:49], 0.5, v[214:215] op_sel_hi:[1,0,1]
	v_pk_fma_f32 v[42:43], v[42:43], 0.5, v[216:217] op_sel_hi:[1,0,1]
	v_pk_fma_f32 v[44:45], v[44:45], 0.5, v[218:219] op_sel_hi:[1,0,1]
	v_pk_fma_f32 v[38:39], v[38:39], 0.5, v[220:221] op_sel_hi:[1,0,1]
	v_pk_fma_f32 v[40:41], v[40:41], 0.5, v[222:223] op_sel_hi:[1,0,1]
	v_pk_fma_f32 v[34:35], v[34:35], 0.5, v[224:225] op_sel_hi:[1,0,1]
	v_pk_fma_f32 v[36:37], v[36:37], 0.5, v[226:227] op_sel_hi:[1,0,1]
	global_store_dwordx4 v[160:161], v[46:49], off
	global_store_dwordx4 v[160:161], v[42:45], off offset:16
	global_store_dwordx4 v[160:161], v[38:41], off offset:512
	global_store_dwordx4 v[160:161], v[34:37], off offset:528
	s_waitcnt vmcnt(12)
	v_pk_fma_f32 v[30:31], v[30:31], 0.5, v[180:181] op_sel_hi:[1,0,1]
	v_pk_fma_f32 v[32:33], v[32:33], 0.5, v[182:183] op_sel_hi:[1,0,1]
	v_pk_fma_f32 v[26:27], v[26:27], 0.5, v[184:185] op_sel_hi:[1,0,1]
	v_pk_fma_f32 v[28:29], v[28:29], 0.5, v[186:187] op_sel_hi:[1,0,1]
	v_pk_fma_f32 v[22:23], v[22:23], 0.5, v[188:189] op_sel_hi:[1,0,1]
	v_pk_fma_f32 v[24:25], v[24:25], 0.5, v[190:191] op_sel_hi:[1,0,1]
	v_pk_fma_f32 v[18:19], v[18:19], 0.5, v[192:193] op_sel_hi:[1,0,1]
	v_pk_fma_f32 v[20:21], v[20:21], 0.5, v[194:195] op_sel_hi:[1,0,1]
	global_store_dwordx4 v[148:149], v[30:33], off
	global_store_dwordx4 v[148:149], v[26:29], off offset:16
	global_store_dwordx4 v[148:149], v[22:25], off offset:512
	global_store_dwordx4 v[148:149], v[18:21], off offset:528
	s_waitcnt vmcnt(8)
	v_pk_fma_f32 v[14:15], v[14:15], 0.5, v[196:197] op_sel_hi:[1,0,1]
	v_pk_fma_f32 v[16:17], v[16:17], 0.5, v[198:199] op_sel_hi:[1,0,1]
	v_pk_fma_f32 v[10:11], v[10:11], 0.5, v[200:201] op_sel_hi:[1,0,1]
	v_pk_fma_f32 v[12:13], v[12:13], 0.5, v[202:203] op_sel_hi:[1,0,1]
	v_pk_fma_f32 v[6:7], v[6:7], 0.5, v[204:205] op_sel_hi:[1,0,1]
	v_pk_fma_f32 v[8:9], v[8:9], 0.5, v[206:207] op_sel_hi:[1,0,1]
	v_pk_fma_f32 v[2:3], v[2:3], 0.5, v[208:209] op_sel_hi:[1,0,1]
	v_pk_fma_f32 v[4:5], v[4:5], 0.5, v[210:211] op_sel_hi:[1,0,1]
	global_store_dwordx4 v[230:231], v[14:17], off
	global_store_dwordx4 v[230:231], v[10:13], off offset:16
	global_store_dwordx4 v[230:231], v[6:9], off offset:512
	global_store_dwordx4 v[230:231], v[2:5], off offset:528
	s_mov_b64 s[26:27], s[24:25]
	s_cbranch_vccz .LBB0_171
	s_waitcnt vmcnt(0)
	v_readlane_b32 s52, v254, 26
	v_readlane_b32 s56, v254, 30
	v_readlane_b32 s54, v254, 32
	s_cmpk_gt_u32 s4, 0xff
	v_readlane_b32 s53, v254, 27
	v_readlane_b32 s57, v254, 31
	v_readlane_b32 s55, v254, 33
	s_mov_b64 s[58:59], s[84:85]
	s_cbranch_scc1 .LBB0_186
	s_barrier

.LBB0_360:
	s_add_u32 s26, s42, 0xfff80080
	s_addc_u32 s27, s43, -1
	s_add_i32 s58, 0, 0x10000
	v_add_u32_e32 v134, s58, v153
	ds_read_b128 v[148:151], v134
	ds_read_b128 v[156:159], v134 offset:1024
	ds_read_b128 v[160:163], v134 offset:2048
	ds_read_b128 v[164:167], v134 offset:3072
	s_cmp_eq_u32 s57, 28
	s_cselect_b32 s45, s23, s27
	s_cselect_b32 s44, s53, s26
	s_cselect_b32 s27, s1, s56
	s_cselect_b32 s26, s54, s55
	s_add_i32 m0, s7, 0xc000
	ds_read_b128 v[180:183], v155
	ds_read_b128 v[184:187], v155 offset:1024
	ds_read_b128 v[188:191], v155 offset:2048
	ds_read_b128 v[192:195], v155 offset:3072
	ds_read_b128 v[196:199], v155 offset:4096
	ds_read_b128 v[200:203], v155 offset:5120
	ds_read_b128 v[204:207], v155 offset:6144
	ds_read_b128 v[208:211], v155 offset:7168
	global_load_lds_dwordx4 v144, s[42:43]
	s_add_i32 m0, s7, 0xe000
	s_nop 0
	global_load_lds_dwordx4 v146, s[42:43]
	s_waitcnt lgkmcnt(8)
	s_barrier
	s_waitcnt lgkmcnt(0)
	s_setprio 1
	s_waitcnt lgkmcnt(0)
	v_mfma_f32_16x16x32_bf16 v[126:129], v[148:151], v[180:183], v[126:129]
	v_mfma_f32_16x16x32_bf16 v[122:125], v[160:163], v[180:183], v[122:125]
	v_mfma_f32_16x16x32_bf16 v[118:121], v[148:151], v[188:191], v[118:121]
	v_mfma_f32_16x16x32_bf16 v[110:113], v[160:163], v[188:191], v[110:113]
	v_mfma_f32_16x16x32_bf16 v[102:105], v[148:151], v[196:199], v[102:105]
	v_mfma_f32_16x16x32_bf16 v[94:97], v[160:163], v[196:199], v[94:97]
	v_mfma_f32_16x16x32_bf16 v[86:89], v[148:151], v[204:207], v[86:89]
	v_mfma_f32_16x16x32_bf16 v[78:81], v[160:163], v[204:207], v[78:81]
	v_mfma_f32_16x16x32_bf16 v[126:129], v[156:159], v[184:187], v[126:129]
	v_mfma_f32_16x16x32_bf16 v[122:125], v[164:167], v[184:187], v[122:125]
	v_mfma_f32_16x16x32_bf16 v[118:121], v[156:159], v[192:195], v[118:121]
	v_mfma_f32_16x16x32_bf16 v[110:113], v[164:167], v[192:195], v[110:113]
	v_mfma_f32_16x16x32_bf16 v[102:105], v[156:159], v[200:203], v[102:105]
	v_mfma_f32_16x16x32_bf16 v[94:97], v[164:167], v[200:203], v[94:97]
	v_mfma_f32_16x16x32_bf16 v[86:89], v[156:159], v[208:211], v[86:89]
	v_mfma_f32_16x16x32_bf16 v[78:81], v[164:167], v[208:211], v[78:81]
	s_setprio 0
	s_barrier
	s_add_i32 s60, 0, 0x14000
	s_add_i32 s58, s58, s6
	ds_read_b128 v[212:215], v134 offset:16384
	ds_read_b128 v[216:219], v134 offset:17408
	ds_read_b128 v[220:223], v134 offset:18432
	ds_read_b128 v[224:227], v134 offset:19456
	s_mov_b32 m0, s58
	global_load_lds_dwordx4 v0, s[26:27]
	s_add_i32 m0, s58, 0x2000
	s_nop 0
	global_load_lds_dwordx4 v138, s[26:27]
	s_barrier
	s_waitcnt lgkmcnt(0)
	s_setprio 1
	s_waitcnt lgkmcnt(0)
	v_mfma_f32_16x16x32_bf16 v[114:117], v[212:215], v[180:183], v[114:117]
	v_mfma_f32_16x16x32_bf16 v[106:109], v[220:223], v[180:183], v[106:109]
	v_mfma_f32_16x16x32_bf16 v[98:101], v[212:215], v[188:191], v[98:101]
	v_mfma_f32_16x16x32_bf16 v[90:93], v[220:223], v[188:191], v[90:93]
	v_mfma_f32_16x16x32_bf16 v[82:85], v[212:215], v[196:199], v[82:85]
	v_mfma_f32_16x16x32_bf16 v[74:77], v[220:223], v[196:199], v[74:77]
	v_mfma_f32_16x16x32_bf16 v[70:73], v[212:215], v[204:207], v[70:73]
	v_mfma_f32_16x16x32_bf16 v[66:69], v[220:223], v[204:207], v[66:69]
	v_mfma_f32_16x16x32_bf16 v[114:117], v[216:219], v[184:187], v[114:117]
	v_mfma_f32_16x16x32_bf16 v[106:109], v[224:227], v[184:187], v[106:109]
	v_mfma_f32_16x16x32_bf16 v[98:101], v[216:219], v[192:195], v[98:101]
	v_mfma_f32_16x16x32_bf16 v[90:93], v[224:227], v[192:195], v[90:93]
	v_mfma_f32_16x16x32_bf16 v[82:85], v[216:219], v[200:203], v[82:85]
	v_mfma_f32_16x16x32_bf16 v[74:77], v[224:227], v[200:203], v[74:77]
	v_mfma_f32_16x16x32_bf16 v[70:73], v[216:219], v[208:211], v[70:73]
	v_mfma_f32_16x16x32_bf16 v[66:69], v[224:227], v[208:211], v[66:69]
	s_setprio 0
	s_mov_b32 m0, s7
	s_add_u32 vcc_lo, s44, s10
	s_addc_u32 vcc_hi, s45, s11
	s_barrier
	ds_read_b128 v[180:183], v155 offset:16384
	ds_read_b128 v[184:187], v155 offset:17408
	ds_read_b128 v[188:191], v155 offset:18432
	ds_read_b128 v[192:195], v155 offset:19456
	ds_read_b128 v[196:199], v155 offset:20480
	ds_read_b128 v[200:203], v155 offset:21504
	ds_read_b128 v[204:207], v155 offset:22528
	ds_read_b128 v[208:211], v155 offset:23552
	global_load_lds_dwordx4 v142, s[44:45]
	s_mov_b32 m0, s14
	s_nop 0
	global_load_lds_dwordx4 v140, s[44:45]
	s_barrier
	s_waitcnt lgkmcnt(0)
	s_setprio 1
	s_waitcnt lgkmcnt(0)
	v_mfma_f32_16x16x32_bf16 v[62:65], v[148:151], v[180:183], v[62:65]
	v_mfma_f32_16x16x32_bf16 v[58:61], v[160:163], v[180:183], v[58:61]
	v_mfma_f32_16x16x32_bf16 v[54:57], v[148:151], v[188:191], v[54:57]
	v_mfma_f32_16x16x32_bf16 v[46:49], v[160:163], v[188:191], v[46:49]
	v_mfma_f32_16x16x32_bf16 v[38:41], v[148:151], v[196:199], v[38:41]
	v_mfma_f32_16x16x32_bf16 v[30:33], v[160:163], v[196:199], v[30:33]
	v_mfma_f32_16x16x32_bf16 v[22:25], v[148:151], v[204:207], v[22:25]
	v_mfma_f32_16x16x32_bf16 v[14:17], v[160:163], v[204:207], v[14:17]
	v_mfma_f32_16x16x32_bf16 v[62:65], v[156:159], v[184:187], v[62:65]
	v_mfma_f32_16x16x32_bf16 v[58:61], v[164:167], v[184:187], v[58:61]
	v_mfma_f32_16x16x32_bf16 v[54:57], v[156:159], v[192:195], v[54:57]
	v_mfma_f32_16x16x32_bf16 v[46:49], v[164:167], v[192:195], v[46:49]
	v_mfma_f32_16x16x32_bf16 v[38:41], v[156:159], v[200:203], v[38:41]
	v_mfma_f32_16x16x32_bf16 v[30:33], v[164:167], v[200:203], v[30:33]
	v_mfma_f32_16x16x32_bf16 v[22:25], v[156:159], v[208:211], v[22:25]
	v_mfma_f32_16x16x32_bf16 v[14:17], v[164:167], v[208:211], v[14:17]
	s_setprio 0
	s_barrier
	s_add_u32 s58, s26, 0x80000
	s_addc_u32 s59, s27, 0
	s_add_i32 s60, s60, s6
	s_mov_b32 m0, s60
	s_nop 0
	global_load_lds_dwordx4 v0, s[58:59]
	s_add_i32 m0, s60, 0x2000
	s_nop 0
	global_load_lds_dwordx4 v138, s[58:59]
	s_waitcnt vmcnt(6)
	s_barrier
	s_setprio 1
	v_mfma_f32_16x16x32_bf16 v[50:53], v[212:215], v[180:183], v[50:53]
	v_mfma_f32_16x16x32_bf16 v[42:45], v[220:223], v[180:183], v[42:45]
	v_mfma_f32_16x16x32_bf16 v[34:37], v[212:215], v[188:191], v[34:37]
	v_mfma_f32_16x16x32_bf16 v[26:29], v[220:223], v[188:191], v[26:29]
	v_mfma_f32_16x16x32_bf16 v[18:21], v[212:215], v[196:199], v[18:21]
	v_mfma_f32_16x16x32_bf16 v[10:13], v[220:223], v[196:199], v[10:13]
	v_mfma_f32_16x16x32_bf16 v[6:9], v[212:215], v[204:207], v[6:9]
	v_mfma_f32_16x16x32_bf16 v[2:5], v[220:223], v[204:207], v[2:5]
	v_mfma_f32_16x16x32_bf16 v[50:53], v[216:219], v[184:187], v[50:53]
	v_mfma_f32_16x16x32_bf16 v[42:45], v[224:227], v[184:187], v[42:45]
	v_mfma_f32_16x16x32_bf16 v[34:37], v[216:219], v[192:195], v[34:37]
	v_mfma_f32_16x16x32_bf16 v[26:29], v[224:227], v[192:195], v[26:29]
	v_mfma_f32_16x16x32_bf16 v[18:21], v[216:219], v[200:203], v[18:21]
	v_mfma_f32_16x16x32_bf16 v[10:13], v[224:227], v[200:203], v[10:13]
	v_mfma_f32_16x16x32_bf16 v[6:9], v[216:219], v[208:211], v[6:9]
	v_mfma_f32_16x16x32_bf16 v[2:5], v[224:227], v[208:211], v[2:5]
	s_setprio 0
	s_add_i32 s58, 0, 0x18000
	s_barrier
	ds_read_b128 v[148:151], v134 offset:32768
	ds_read_b128 v[156:159], v134 offset:33792
	ds_read_b128 v[160:163], v134 offset:34816
	ds_read_b128 v[164:167], v134 offset:35840
	s_add_u32 s44, s44, 0x80000
	s_addc_u32 s45, s45, 0
	s_mov_b32 m0, s46
	ds_read_b128 v[180:183], v155 offset:32768
	ds_read_b128 v[184:187], v155 offset:33792
	ds_read_b128 v[188:191], v155 offset:34816
	ds_read_b128 v[192:195], v155 offset:35840
	ds_read_b128 v[196:199], v155 offset:36864
	ds_read_b128 v[200:203], v155 offset:37888
	ds_read_b128 v[204:207], v155 offset:38912
	ds_read_b128 v[208:211], v155 offset:39936
	global_load_lds_dwordx4 v142, s[44:45]
	s_mov_b32 m0, s47
	s_nop 0
	global_load_lds_dwordx4 v140, s[44:45]
	s_waitcnt lgkmcnt(8)
	s_barrier
	s_waitcnt lgkmcnt(0)
	s_setprio 1
	s_waitcnt lgkmcnt(0)
	v_mfma_f32_16x16x32_bf16 v[126:129], v[148:151], v[180:183], v[126:129]
	v_mfma_f32_16x16x32_bf16 v[122:125], v[160:163], v[180:183], v[122:125]
	v_mfma_f32_16x16x32_bf16 v[118:121], v[148:151], v[188:191], v[118:121]
	v_mfma_f32_16x16x32_bf16 v[110:113], v[160:163], v[188:191], v[110:113]
	v_mfma_f32_16x16x32_bf16 v[102:105], v[148:151], v[196:199], v[102:105]
	v_mfma_f32_16x16x32_bf16 v[94:97], v[160:163], v[196:199], v[94:97]
	v_mfma_f32_16x16x32_bf16 v[86:89], v[148:151], v[204:207], v[86:89]
	v_mfma_f32_16x16x32_bf16 v[78:81], v[160:163], v[204:207], v[78:81]
	v_mfma_f32_16x16x32_bf16 v[126:129], v[156:159], v[184:187], v[126:129]
	v_mfma_f32_16x16x32_bf16 v[122:125], v[164:167], v[184:187], v[122:125]
	v_mfma_f32_16x16x32_bf16 v[118:121], v[156:159], v[192:195], v[118:121]
	v_mfma_f32_16x16x32_bf16 v[110:113], v[164:167], v[192:195], v[110:113]
	v_mfma_f32_16x16x32_bf16 v[102:105], v[156:159], v[200:203], v[102:105]
	v_mfma_f32_16x16x32_bf16 v[94:97], v[164:167], v[200:203], v[94:97]
	v_mfma_f32_16x16x32_bf16 v[86:89], v[156:159], v[208:211], v[86:89]
	v_mfma_f32_16x16x32_bf16 v[78:81], v[164:167], v[208:211], v[78:81]
	s_setprio 0
	s_barrier
	s_add_i32 s44, 0, 0x1c000
	s_add_i32 s45, s58, s6
	s_add_u32 s100, s26, s10
	s_addc_u32 s101, s27, s11
	s_mov_b32 m0, s45
	ds_read_b128 v[212:215], v134 offset:49152
	ds_read_b128 v[216:219], v134 offset:50176
	ds_read_b128 v[220:223], v134 offset:51200
	ds_read_b128 v[224:227], v134 offset:52224
	global_load_lds_dwordx4 v0, s[100:101]
	s_add_u32 s100, s26, s10
	s_addc_u32 s101, s27, s11
	s_add_i32 m0, s45, 0x2000
	s_nop 0
	global_load_lds_dwordx4 v138, s[100:101]
	s_barrier
	s_waitcnt lgkmcnt(0)
	s_setprio 1
	s_waitcnt lgkmcnt(0)
	v_mfma_f32_16x16x32_bf16 v[114:117], v[212:215], v[180:183], v[114:117]
	v_mfma_f32_16x16x32_bf16 v[106:109], v[220:223], v[180:183], v[106:109]
	v_mfma_f32_16x16x32_bf16 v[98:101], v[212:215], v[188:191], v[98:101]
	v_mfma_f32_16x16x32_bf16 v[90:93], v[220:223], v[188:191], v[90:93]
	v_mfma_f32_16x16x32_bf16 v[82:85], v[212:215], v[196:199], v[82:85]
	v_mfma_f32_16x16x32_bf16 v[74:77], v[220:223], v[196:199], v[74:77]
	v_mfma_f32_16x16x32_bf16 v[70:73], v[212:215], v[204:207], v[70:73]
	v_mfma_f32_16x16x32_bf16 v[66:69], v[220:223], v[204:207], v[66:69]
	v_mfma_f32_16x16x32_bf16 v[114:117], v[216:219], v[184:187], v[114:117]
	v_mfma_f32_16x16x32_bf16 v[106:109], v[224:227], v[184:187], v[106:109]
	v_mfma_f32_16x16x32_bf16 v[98:101], v[216:219], v[192:195], v[98:101]
	v_mfma_f32_16x16x32_bf16 v[90:93], v[224:227], v[192:195], v[90:93]
	v_mfma_f32_16x16x32_bf16 v[82:85], v[216:219], v[200:203], v[82:85]
	v_mfma_f32_16x16x32_bf16 v[74:77], v[224:227], v[200:203], v[74:77]
	v_mfma_f32_16x16x32_bf16 v[70:73], v[216:219], v[208:211], v[70:73]
	v_mfma_f32_16x16x32_bf16 v[66:69], v[224:227], v[208:211], v[66:69]
	s_setprio 0
	s_mov_b32 m0, s48
	s_barrier
	ds_read_b128 v[180:183], v155 offset:49152
	ds_read_b128 v[184:187], v155 offset:50176
	ds_read_b128 v[188:191], v155 offset:51200
	ds_read_b128 v[192:195], v155 offset:52224
	ds_read_b128 v[196:199], v155 offset:53248
	ds_read_b128 v[200:203], v155 offset:54272
	ds_read_b128 v[204:207], v155 offset:55296
	ds_read_b128 v[208:211], v155 offset:56320
	global_load_lds_dwordx4 v142, vcc
	s_mov_b32 m0, s49
	s_nop 0
	global_load_lds_dwordx4 v140, vcc
	s_barrier
	s_waitcnt lgkmcnt(0)
	s_setprio 1
	s_waitcnt lgkmcnt(0)
	v_mfma_f32_16x16x32_bf16 v[62:65], v[148:151], v[180:183], v[62:65]
	v_mfma_f32_16x16x32_bf16 v[58:61], v[160:163], v[180:183], v[58:61]
	v_mfma_f32_16x16x32_bf16 v[54:57], v[148:151], v[188:191], v[54:57]
	v_mfma_f32_16x16x32_bf16 v[46:49], v[160:163], v[188:191], v[46:49]
	v_mfma_f32_16x16x32_bf16 v[38:41], v[148:151], v[196:199], v[38:41]
	v_mfma_f32_16x16x32_bf16 v[30:33], v[160:163], v[196:199], v[30:33]
	v_mfma_f32_16x16x32_bf16 v[22:25], v[148:151], v[204:207], v[22:25]
	v_mfma_f32_16x16x32_bf16 v[14:17], v[160:163], v[204:207], v[14:17]
	v_mfma_f32_16x16x32_bf16 v[62:65], v[156:159], v[184:187], v[62:65]
	v_mfma_f32_16x16x32_bf16 v[58:61], v[164:167], v[184:187], v[58:61]
	v_mfma_f32_16x16x32_bf16 v[54:57], v[156:159], v[192:195], v[54:57]
	v_mfma_f32_16x16x32_bf16 v[46:49], v[164:167], v[192:195], v[46:49]
	v_mfma_f32_16x16x32_bf16 v[38:41], v[156:159], v[200:203], v[38:41]
	v_mfma_f32_16x16x32_bf16 v[30:33], v[164:167], v[200:203], v[30:33]
	v_mfma_f32_16x16x32_bf16 v[22:25], v[156:159], v[208:211], v[22:25]
	v_mfma_f32_16x16x32_bf16 v[14:17], v[164:167], v[208:211], v[14:17]
	s_setprio 0
	s_barrier
	s_add_u32 s26, s26, 0x80080
	s_addc_u32 s27, s27, 0
	s_add_i32 s44, s44, s6
	s_mov_b32 m0, s44
	s_nop 0
	global_load_lds_dwordx4 v0, s[26:27]
	s_add_i32 m0, s44, 0x2000
	s_nop 0
	global_load_lds_dwordx4 v138, s[26:27]
	s_waitcnt vmcnt(6)
	s_barrier
	s_setprio 1
	v_mfma_f32_16x16x32_bf16 v[50:53], v[212:215], v[180:183], v[50:53]
	v_mfma_f32_16x16x32_bf16 v[42:45], v[220:223], v[180:183], v[42:45]
	v_mfma_f32_16x16x32_bf16 v[34:37], v[212:215], v[188:191], v[34:37]
	v_mfma_f32_16x16x32_bf16 v[26:29], v[220:223], v[188:191], v[26:29]
	v_mfma_f32_16x16x32_bf16 v[18:21], v[212:215], v[196:199], v[18:21]
	v_mfma_f32_16x16x32_bf16 v[10:13], v[220:223], v[196:199], v[10:13]
	v_mfma_f32_16x16x32_bf16 v[6:9], v[212:215], v[204:207], v[6:9]
	v_mfma_f32_16x16x32_bf16 v[2:5], v[220:223], v[204:207], v[2:5]
	v_mfma_f32_16x16x32_bf16 v[50:53], v[216:219], v[184:187], v[50:53]
	v_mfma_f32_16x16x32_bf16 v[42:45], v[224:227], v[184:187], v[42:45]
	v_mfma_f32_16x16x32_bf16 v[34:37], v[216:219], v[192:195], v[34:37]
	v_mfma_f32_16x16x32_bf16 v[26:29], v[224:227], v[192:195], v[26:29]
	v_mfma_f32_16x16x32_bf16 v[18:21], v[216:219], v[200:203], v[18:21]
	v_mfma_f32_16x16x32_bf16 v[10:13], v[224:227], v[200:203], v[10:13]
	v_mfma_f32_16x16x32_bf16 v[6:9], v[216:219], v[208:211], v[6:9]
	v_mfma_f32_16x16x32_bf16 v[2:5], v[224:227], v[208:211], v[2:5]
	s_setprio 0
	s_add_i32 s57, s57, 2
	s_add_u32 s42, s42, 0x100
	s_addc_u32 s43, s43, 0
	s_add_u32 s55, s55, 0x100
	s_addc_u32 s56, s56, 0
	s_cmp_gt_u32 s57, 29
	s_barrier
	s_cbranch_scc0 .LBB0_360
	v_lshl_or_b32 v134, s51, 8, v154
	v_lshl_add_u32 v158, s52, 8, v152
	v_ashrrev_i32_e32 v135, 31, v134
	v_mov_b64_e32 v[148:149], s[88:89]
	v_mad_i64_i32 v[156:157], s[26:27], v158, s35, v[148:149]
	v_lshlrev_b64 v[150:151], 1, v[134:135]
	v_lshl_add_u64 v[134:135], v[156:157], 0, v[150:151]
	v_cvt_pk_bf16_f32 v126, v126, v127
	v_cvt_pk_bf16_f32 v127, v128, v129
	v_cvt_pk_bf16_f32 v128, v122, v123
	v_cvt_pk_bf16_f32 v129, v124, v125
	global_store_dwordx4 v[134:135], v[126:129], off
	v_cvt_pk_bf16_f32 v114, v114, v115
	v_cvt_pk_bf16_f32 v115, v116, v117
	v_cvt_pk_bf16_f32 v116, v106, v107
	v_or_b32_e32 v106, 16, v158
	v_mad_i64_i32 v[106:107], s[26:27], v106, s35, v[148:149]
	v_cvt_pk_bf16_f32 v117, v108, v109
	global_store_dwordx4 v[134:135], v[114:117], off offset:256
	s_and_b64 vcc, exec, s[40:41]
	s_mov_b32 s51, s0
	v_lshl_add_u64 v[114:115], v[106:107], 0, v[150:151]
	v_cvt_pk_bf16_f32 v106, v118, v119
	v_cvt_pk_bf16_f32 v107, v120, v121
	v_cvt_pk_bf16_f32 v108, v110, v111
	v_cvt_pk_bf16_f32 v109, v112, v113
	global_store_dwordx4 v[114:115], v[106:109], off
	v_cvt_pk_bf16_f32 v98, v98, v99
	v_cvt_pk_bf16_f32 v99, v100, v101
	v_cvt_pk_bf16_f32 v100, v90, v91
	v_or_b32_e32 v90, 32, v158
	v_mad_i64_i32 v[90:91], s[26:27], v90, s35, v[148:149]
	v_cvt_pk_bf16_f32 v101, v92, v93
	global_store_dwordx4 v[114:115], v[98:101], off offset:256
	s_mov_b32 s52, s22
	s_mov_b64 s[42:43], s[24:25]
	v_lshl_add_u64 v[98:99], v[90:91], 0, v[150:151]
	v_cvt_pk_bf16_f32 v90, v102, v103
	v_cvt_pk_bf16_f32 v91, v104, v105
	v_cvt_pk_bf16_f32 v92, v94, v95
	v_cvt_pk_bf16_f32 v93, v96, v97
	global_store_dwordx4 v[98:99], v[90:93], off
	v_cvt_pk_bf16_f32 v82, v82, v83
	v_cvt_pk_bf16_f32 v83, v84, v85
	v_cvt_pk_bf16_f32 v84, v74, v75
	v_or_b32_e32 v74, 48, v158
	v_mad_i64_i32 v[74:75], s[26:27], v74, s35, v[148:149]
	v_cvt_pk_bf16_f32 v85, v76, v77
	global_store_dwordx4 v[98:99], v[82:85], off offset:256
	s_nop 1
	v_lshl_add_u64 v[82:83], v[74:75], 0, v[150:151]
	v_cvt_pk_bf16_f32 v74, v86, v87
	v_cvt_pk_bf16_f32 v75, v88, v89
	v_cvt_pk_bf16_f32 v76, v78, v79
	v_cvt_pk_bf16_f32 v77, v80, v81
	global_store_dwordx4 v[82:83], v[74:77], off
	v_cvt_pk_bf16_f32 v70, v70, v71
	v_cvt_pk_bf16_f32 v71, v72, v73
	v_cvt_pk_bf16_f32 v72, v66, v67
	v_add_u32_e32 v66, 0x80, v158
	v_mad_i64_i32 v[66:67], s[26:27], v66, s35, v[148:149]
	v_lshl_add_u64 v[66:67], v[66:67], 0, v[150:151]
	v_cvt_pk_bf16_f32 v73, v68, v69
	global_store_dwordx4 v[82:83], v[70:73], off offset:256
	v_cvt_pk_bf16_f32 v62, v62, v63
	v_cvt_pk_bf16_f32 v63, v64, v65
	v_cvt_pk_bf16_f32 v64, v58, v59
	v_cvt_pk_bf16_f32 v65, v60, v61
	global_store_dwordx4 v[66:67], v[62:65], off
	v_cvt_pk_bf16_f32 v50, v50, v51
	v_cvt_pk_bf16_f32 v51, v52, v53
	v_cvt_pk_bf16_f32 v52, v42, v43
	v_add_u32_e32 v42, 0x90, v158
	v_mad_i64_i32 v[42:43], s[26:27], v42, s35, v[148:149]
	v_cvt_pk_bf16_f32 v53, v44, v45
	global_store_dwordx4 v[66:67], v[50:53], off offset:256
	s_nop 1
	v_lshl_add_u64 v[50:51], v[42:43], 0, v[150:151]
	v_cvt_pk_bf16_f32 v42, v54, v55
	v_cvt_pk_bf16_f32 v43, v56, v57
	v_cvt_pk_bf16_f32 v44, v46, v47
	v_cvt_pk_bf16_f32 v45, v48, v49
	global_store_dwordx4 v[50:51], v[42:45], off
	v_cvt_pk_bf16_f32 v34, v34, v35
	v_cvt_pk_bf16_f32 v35, v36, v37
	v_cvt_pk_bf16_f32 v36, v26, v27
	v_add_u32_e32 v26, 0xa0, v158
	v_mad_i64_i32 v[26:27], s[26:27], v26, s35, v[148:149]
	v_cvt_pk_bf16_f32 v37, v28, v29
	global_store_dwordx4 v[50:51], v[34:37], off offset:256
	s_nop 1
	v_lshl_add_u64 v[34:35], v[26:27], 0, v[150:151]
	v_cvt_pk_bf16_f32 v26, v38, v39
	v_cvt_pk_bf16_f32 v27, v40, v41
	v_cvt_pk_bf16_f32 v28, v30, v31
	v_cvt_pk_bf16_f32 v29, v32, v33
	global_store_dwordx4 v[34:35], v[26:29], off
	v_cvt_pk_bf16_f32 v18, v18, v19
	v_cvt_pk_bf16_f32 v19, v20, v21
	v_cvt_pk_bf16_f32 v20, v10, v11
	v_add_u32_e32 v10, 0xb0, v158
	v_mad_i64_i32 v[10:11], s[26:27], v10, s35, v[148:149]
	v_cvt_pk_bf16_f32 v21, v12, v13
	global_store_dwordx4 v[34:35], v[18:21], off offset:256
	s_mov_b64 s[26:27], s[38:39]
	s_nop 0
	v_lshl_add_u64 v[18:19], v[10:11], 0, v[150:151]
	v_cvt_pk_bf16_f32 v10, v22, v23
	v_cvt_pk_bf16_f32 v11, v24, v25
	v_cvt_pk_bf16_f32 v12, v14, v15
	v_cvt_pk_bf16_f32 v13, v16, v17
	global_store_dwordx4 v[18:19], v[10:13], off
	v_cvt_pk_bf16_f32 v6, v6, v7
	v_cvt_pk_bf16_f32 v7, v8, v9
	v_cvt_pk_bf16_f32 v8, v2, v3
	v_cvt_pk_bf16_f32 v9, v4, v5
	global_store_dwordx4 v[18:19], v[6:9], off offset:256
	s_cbranch_vccz .LBB0_357
	s_waitcnt vmcnt(0)
	v_readlane_b32 s52, v254, 26
	v_readlane_b32 s50, v254, 28
	s_cmpk_gt_u32 s4, 0xff
	v_readlane_b32 s53, v254, 27
	v_readlane_b32 s51, v254, 29
	s_cbranch_scc1 .LBB0_364
	s_barrier

.LBB0_627:
	s_add_u32 s26, s42, 0xfff80080
	s_addc_u32 s27, s43, -1
	s_add_i32 s58, 0, 0x10000
	v_add_u32_e32 v134, s58, v153
	ds_read_b128 v[148:151], v134
	ds_read_b128 v[156:159], v134 offset:1024
	ds_read_b128 v[160:163], v134 offset:2048
	ds_read_b128 v[164:167], v134 offset:3072
	s_cmp_eq_u32 s57, 28
	s_cselect_b32 s45, s23, s27
	s_cselect_b32 s44, s53, s26
	s_cselect_b32 s27, s1, s56
	s_cselect_b32 s26, s54, s55
	s_add_i32 m0, s7, 0xc000
	ds_read_b128 v[180:183], v155
	ds_read_b128 v[184:187], v155 offset:1024
	ds_read_b128 v[188:191], v155 offset:2048
	ds_read_b128 v[192:195], v155 offset:3072
	ds_read_b128 v[196:199], v155 offset:4096
	ds_read_b128 v[200:203], v155 offset:5120
	ds_read_b128 v[204:207], v155 offset:6144
	ds_read_b128 v[208:211], v155 offset:7168
	global_load_lds_dwordx4 v144, s[42:43]
	s_add_i32 m0, s7, 0xe000
	s_nop 0
	global_load_lds_dwordx4 v146, s[42:43]
	s_waitcnt lgkmcnt(8)
	s_barrier
	s_waitcnt lgkmcnt(0)
	s_setprio 1
	s_waitcnt lgkmcnt(0)
	v_mfma_f32_16x16x32_bf16 v[126:129], v[148:151], v[180:183], v[126:129]
	v_mfma_f32_16x16x32_bf16 v[122:125], v[160:163], v[180:183], v[122:125]
	v_mfma_f32_16x16x32_bf16 v[118:121], v[148:151], v[188:191], v[118:121]
	v_mfma_f32_16x16x32_bf16 v[110:113], v[160:163], v[188:191], v[110:113]
	v_mfma_f32_16x16x32_bf16 v[102:105], v[148:151], v[196:199], v[102:105]
	v_mfma_f32_16x16x32_bf16 v[94:97], v[160:163], v[196:199], v[94:97]
	v_mfma_f32_16x16x32_bf16 v[86:89], v[148:151], v[204:207], v[86:89]
	v_mfma_f32_16x16x32_bf16 v[78:81], v[160:163], v[204:207], v[78:81]
	v_mfma_f32_16x16x32_bf16 v[126:129], v[156:159], v[184:187], v[126:129]
	v_mfma_f32_16x16x32_bf16 v[122:125], v[164:167], v[184:187], v[122:125]
	v_mfma_f32_16x16x32_bf16 v[118:121], v[156:159], v[192:195], v[118:121]
	v_mfma_f32_16x16x32_bf16 v[110:113], v[164:167], v[192:195], v[110:113]
	v_mfma_f32_16x16x32_bf16 v[102:105], v[156:159], v[200:203], v[102:105]
	v_mfma_f32_16x16x32_bf16 v[94:97], v[164:167], v[200:203], v[94:97]
	v_mfma_f32_16x16x32_bf16 v[86:89], v[156:159], v[208:211], v[86:89]
	v_mfma_f32_16x16x32_bf16 v[78:81], v[164:167], v[208:211], v[78:81]
	s_setprio 0
	s_barrier
	s_add_i32 s60, 0, 0x14000
	s_add_i32 s58, s58, s6
	ds_read_b128 v[212:215], v134 offset:16384
	ds_read_b128 v[216:219], v134 offset:17408
	ds_read_b128 v[220:223], v134 offset:18432
	ds_read_b128 v[224:227], v134 offset:19456
	s_mov_b32 m0, s58
	global_load_lds_dwordx4 v0, s[26:27]
	s_add_i32 m0, s58, 0x2000
	s_nop 0
	global_load_lds_dwordx4 v138, s[26:27]
	s_barrier
	s_waitcnt lgkmcnt(0)
	s_setprio 1
	s_waitcnt lgkmcnt(0)
	v_mfma_f32_16x16x32_bf16 v[114:117], v[212:215], v[180:183], v[114:117]
	v_mfma_f32_16x16x32_bf16 v[106:109], v[220:223], v[180:183], v[106:109]
	v_mfma_f32_16x16x32_bf16 v[98:101], v[212:215], v[188:191], v[98:101]
	v_mfma_f32_16x16x32_bf16 v[90:93], v[220:223], v[188:191], v[90:93]
	v_mfma_f32_16x16x32_bf16 v[82:85], v[212:215], v[196:199], v[82:85]
	v_mfma_f32_16x16x32_bf16 v[74:77], v[220:223], v[196:199], v[74:77]
	v_mfma_f32_16x16x32_bf16 v[70:73], v[212:215], v[204:207], v[70:73]
	v_mfma_f32_16x16x32_bf16 v[66:69], v[220:223], v[204:207], v[66:69]
	v_mfma_f32_16x16x32_bf16 v[114:117], v[216:219], v[184:187], v[114:117]
	v_mfma_f32_16x16x32_bf16 v[106:109], v[224:227], v[184:187], v[106:109]
	v_mfma_f32_16x16x32_bf16 v[98:101], v[216:219], v[192:195], v[98:101]
	v_mfma_f32_16x16x32_bf16 v[90:93], v[224:227], v[192:195], v[90:93]
	v_mfma_f32_16x16x32_bf16 v[82:85], v[216:219], v[200:203], v[82:85]
	v_mfma_f32_16x16x32_bf16 v[74:77], v[224:227], v[200:203], v[74:77]
	v_mfma_f32_16x16x32_bf16 v[70:73], v[216:219], v[208:211], v[70:73]
	v_mfma_f32_16x16x32_bf16 v[66:69], v[224:227], v[208:211], v[66:69]
	s_setprio 0
	s_mov_b32 m0, s7
	s_add_u32 vcc_lo, s44, s10
	s_addc_u32 vcc_hi, s45, s11
	s_barrier
	ds_read_b128 v[180:183], v155 offset:16384
	ds_read_b128 v[184:187], v155 offset:17408
	ds_read_b128 v[188:191], v155 offset:18432
	ds_read_b128 v[192:195], v155 offset:19456
	ds_read_b128 v[196:199], v155 offset:20480
	ds_read_b128 v[200:203], v155 offset:21504
	ds_read_b128 v[204:207], v155 offset:22528
	ds_read_b128 v[208:211], v155 offset:23552
	global_load_lds_dwordx4 v142, s[44:45]
	s_mov_b32 m0, s14
	s_nop 0
	global_load_lds_dwordx4 v140, s[44:45]
	s_barrier
	s_waitcnt lgkmcnt(0)
	s_setprio 1
	s_waitcnt lgkmcnt(0)
	v_mfma_f32_16x16x32_bf16 v[62:65], v[148:151], v[180:183], v[62:65]
	v_mfma_f32_16x16x32_bf16 v[58:61], v[160:163], v[180:183], v[58:61]
	v_mfma_f32_16x16x32_bf16 v[54:57], v[148:151], v[188:191], v[54:57]
	v_mfma_f32_16x16x32_bf16 v[46:49], v[160:163], v[188:191], v[46:49]
	v_mfma_f32_16x16x32_bf16 v[38:41], v[148:151], v[196:199], v[38:41]
	v_mfma_f32_16x16x32_bf16 v[30:33], v[160:163], v[196:199], v[30:33]
	v_mfma_f32_16x16x32_bf16 v[22:25], v[148:151], v[204:207], v[22:25]
	v_mfma_f32_16x16x32_bf16 v[14:17], v[160:163], v[204:207], v[14:17]
	v_mfma_f32_16x16x32_bf16 v[62:65], v[156:159], v[184:187], v[62:65]
	v_mfma_f32_16x16x32_bf16 v[58:61], v[164:167], v[184:187], v[58:61]
	v_mfma_f32_16x16x32_bf16 v[54:57], v[156:159], v[192:195], v[54:57]
	v_mfma_f32_16x16x32_bf16 v[46:49], v[164:167], v[192:195], v[46:49]
	v_mfma_f32_16x16x32_bf16 v[38:41], v[156:159], v[200:203], v[38:41]
	v_mfma_f32_16x16x32_bf16 v[30:33], v[164:167], v[200:203], v[30:33]
	v_mfma_f32_16x16x32_bf16 v[22:25], v[156:159], v[208:211], v[22:25]
	v_mfma_f32_16x16x32_bf16 v[14:17], v[164:167], v[208:211], v[14:17]
	s_setprio 0
	s_barrier
	s_add_u32 s58, s26, 0x80000
	s_addc_u32 s59, s27, 0
	s_add_i32 s60, s60, s6
	s_mov_b32 m0, s60
	s_nop 0
	global_load_lds_dwordx4 v0, s[58:59]
	s_add_i32 m0, s60, 0x2000
	s_nop 0
	global_load_lds_dwordx4 v138, s[58:59]
	s_waitcnt vmcnt(6)
	s_barrier
	s_setprio 1
	v_mfma_f32_16x16x32_bf16 v[50:53], v[212:215], v[180:183], v[50:53]
	v_mfma_f32_16x16x32_bf16 v[42:45], v[220:223], v[180:183], v[42:45]
	v_mfma_f32_16x16x32_bf16 v[34:37], v[212:215], v[188:191], v[34:37]
	v_mfma_f32_16x16x32_bf16 v[26:29], v[220:223], v[188:191], v[26:29]
	v_mfma_f32_16x16x32_bf16 v[18:21], v[212:215], v[196:199], v[18:21]
	v_mfma_f32_16x16x32_bf16 v[10:13], v[220:223], v[196:199], v[10:13]
	v_mfma_f32_16x16x32_bf16 v[6:9], v[212:215], v[204:207], v[6:9]
	v_mfma_f32_16x16x32_bf16 v[2:5], v[220:223], v[204:207], v[2:5]
	v_mfma_f32_16x16x32_bf16 v[50:53], v[216:219], v[184:187], v[50:53]
	v_mfma_f32_16x16x32_bf16 v[42:45], v[224:227], v[184:187], v[42:45]
	v_mfma_f32_16x16x32_bf16 v[34:37], v[216:219], v[192:195], v[34:37]
	v_mfma_f32_16x16x32_bf16 v[26:29], v[224:227], v[192:195], v[26:29]
	v_mfma_f32_16x16x32_bf16 v[18:21], v[216:219], v[200:203], v[18:21]
	v_mfma_f32_16x16x32_bf16 v[10:13], v[224:227], v[200:203], v[10:13]
	v_mfma_f32_16x16x32_bf16 v[6:9], v[216:219], v[208:211], v[6:9]
	v_mfma_f32_16x16x32_bf16 v[2:5], v[224:227], v[208:211], v[2:5]
	s_setprio 0
	s_add_i32 s58, 0, 0x18000
	s_barrier
	ds_read_b128 v[148:151], v134 offset:32768
	ds_read_b128 v[156:159], v134 offset:33792
	ds_read_b128 v[160:163], v134 offset:34816
	ds_read_b128 v[164:167], v134 offset:35840
	s_add_u32 s44, s44, 0x80000
	s_addc_u32 s45, s45, 0
	s_mov_b32 m0, s46
	ds_read_b128 v[180:183], v155 offset:32768
	ds_read_b128 v[184:187], v155 offset:33792
	ds_read_b128 v[188:191], v155 offset:34816
	ds_read_b128 v[192:195], v155 offset:35840
	ds_read_b128 v[196:199], v155 offset:36864
	ds_read_b128 v[200:203], v155 offset:37888
	ds_read_b128 v[204:207], v155 offset:38912
	ds_read_b128 v[208:211], v155 offset:39936
	global_load_lds_dwordx4 v142, s[44:45]
	s_mov_b32 m0, s47
	s_nop 0
	global_load_lds_dwordx4 v140, s[44:45]
	s_waitcnt lgkmcnt(8)
	s_barrier
	s_waitcnt lgkmcnt(0)
	s_setprio 1
	s_waitcnt lgkmcnt(0)
	v_mfma_f32_16x16x32_bf16 v[126:129], v[148:151], v[180:183], v[126:129]
	v_mfma_f32_16x16x32_bf16 v[122:125], v[160:163], v[180:183], v[122:125]
	v_mfma_f32_16x16x32_bf16 v[118:121], v[148:151], v[188:191], v[118:121]
	v_mfma_f32_16x16x32_bf16 v[110:113], v[160:163], v[188:191], v[110:113]
	v_mfma_f32_16x16x32_bf16 v[102:105], v[148:151], v[196:199], v[102:105]
	v_mfma_f32_16x16x32_bf16 v[94:97], v[160:163], v[196:199], v[94:97]
	v_mfma_f32_16x16x32_bf16 v[86:89], v[148:151], v[204:207], v[86:89]
	v_mfma_f32_16x16x32_bf16 v[78:81], v[160:163], v[204:207], v[78:81]
	v_mfma_f32_16x16x32_bf16 v[126:129], v[156:159], v[184:187], v[126:129]
	v_mfma_f32_16x16x32_bf16 v[122:125], v[164:167], v[184:187], v[122:125]
	v_mfma_f32_16x16x32_bf16 v[118:121], v[156:159], v[192:195], v[118:121]
	v_mfma_f32_16x16x32_bf16 v[110:113], v[164:167], v[192:195], v[110:113]
	v_mfma_f32_16x16x32_bf16 v[102:105], v[156:159], v[200:203], v[102:105]
	v_mfma_f32_16x16x32_bf16 v[94:97], v[164:167], v[200:203], v[94:97]
	v_mfma_f32_16x16x32_bf16 v[86:89], v[156:159], v[208:211], v[86:89]
	v_mfma_f32_16x16x32_bf16 v[78:81], v[164:167], v[208:211], v[78:81]
	s_setprio 0
	s_barrier
	s_add_i32 s44, 0, 0x1c000
	s_add_i32 s45, s58, s6
	s_add_u32 s100, s26, s10
	s_addc_u32 s101, s27, s11
	s_mov_b32 m0, s45
	ds_read_b128 v[212:215], v134 offset:49152
	ds_read_b128 v[216:219], v134 offset:50176
	ds_read_b128 v[220:223], v134 offset:51200
	ds_read_b128 v[224:227], v134 offset:52224
	global_load_lds_dwordx4 v0, s[100:101]
	s_add_u32 s100, s26, s10
	s_addc_u32 s101, s27, s11
	s_add_i32 m0, s45, 0x2000
	s_nop 0
	global_load_lds_dwordx4 v138, s[100:101]
	s_barrier
	s_waitcnt lgkmcnt(0)
	s_setprio 1
	s_waitcnt lgkmcnt(0)
	v_mfma_f32_16x16x32_bf16 v[114:117], v[212:215], v[180:183], v[114:117]
	v_mfma_f32_16x16x32_bf16 v[106:109], v[220:223], v[180:183], v[106:109]
	v_mfma_f32_16x16x32_bf16 v[98:101], v[212:215], v[188:191], v[98:101]
	v_mfma_f32_16x16x32_bf16 v[90:93], v[220:223], v[188:191], v[90:93]
	v_mfma_f32_16x16x32_bf16 v[82:85], v[212:215], v[196:199], v[82:85]
	v_mfma_f32_16x16x32_bf16 v[74:77], v[220:223], v[196:199], v[74:77]
	v_mfma_f32_16x16x32_bf16 v[70:73], v[212:215], v[204:207], v[70:73]
	v_mfma_f32_16x16x32_bf16 v[66:69], v[220:223], v[204:207], v[66:69]
	v_mfma_f32_16x16x32_bf16 v[114:117], v[216:219], v[184:187], v[114:117]
	v_mfma_f32_16x16x32_bf16 v[106:109], v[224:227], v[184:187], v[106:109]
	v_mfma_f32_16x16x32_bf16 v[98:101], v[216:219], v[192:195], v[98:101]
	v_mfma_f32_16x16x32_bf16 v[90:93], v[224:227], v[192:195], v[90:93]
	v_mfma_f32_16x16x32_bf16 v[82:85], v[216:219], v[200:203], v[82:85]
	v_mfma_f32_16x16x32_bf16 v[74:77], v[224:227], v[200:203], v[74:77]
	v_mfma_f32_16x16x32_bf16 v[70:73], v[216:219], v[208:211], v[70:73]
	v_mfma_f32_16x16x32_bf16 v[66:69], v[224:227], v[208:211], v[66:69]
	s_setprio 0
	s_mov_b32 m0, s48
	s_barrier
	ds_read_b128 v[180:183], v155 offset:49152
	ds_read_b128 v[184:187], v155 offset:50176
	ds_read_b128 v[188:191], v155 offset:51200
	ds_read_b128 v[192:195], v155 offset:52224
	ds_read_b128 v[196:199], v155 offset:53248
	ds_read_b128 v[200:203], v155 offset:54272
	ds_read_b128 v[204:207], v155 offset:55296
	ds_read_b128 v[208:211], v155 offset:56320
	global_load_lds_dwordx4 v142, vcc
	s_mov_b32 m0, s49
	s_nop 0
	global_load_lds_dwordx4 v140, vcc
	s_barrier
	s_waitcnt lgkmcnt(0)
	s_setprio 1
	s_waitcnt lgkmcnt(0)
	v_mfma_f32_16x16x32_bf16 v[62:65], v[148:151], v[180:183], v[62:65]
	v_mfma_f32_16x16x32_bf16 v[58:61], v[160:163], v[180:183], v[58:61]
	v_mfma_f32_16x16x32_bf16 v[54:57], v[148:151], v[188:191], v[54:57]
	v_mfma_f32_16x16x32_bf16 v[46:49], v[160:163], v[188:191], v[46:49]
	v_mfma_f32_16x16x32_bf16 v[38:41], v[148:151], v[196:199], v[38:41]
	v_mfma_f32_16x16x32_bf16 v[30:33], v[160:163], v[196:199], v[30:33]
	v_mfma_f32_16x16x32_bf16 v[22:25], v[148:151], v[204:207], v[22:25]
	v_mfma_f32_16x16x32_bf16 v[14:17], v[160:163], v[204:207], v[14:17]
	v_mfma_f32_16x16x32_bf16 v[62:65], v[156:159], v[184:187], v[62:65]
	v_mfma_f32_16x16x32_bf16 v[58:61], v[164:167], v[184:187], v[58:61]
	v_mfma_f32_16x16x32_bf16 v[54:57], v[156:159], v[192:195], v[54:57]
	v_mfma_f32_16x16x32_bf16 v[46:49], v[164:167], v[192:195], v[46:49]
	v_mfma_f32_16x16x32_bf16 v[38:41], v[156:159], v[200:203], v[38:41]
	v_mfma_f32_16x16x32_bf16 v[30:33], v[164:167], v[200:203], v[30:33]
	v_mfma_f32_16x16x32_bf16 v[22:25], v[156:159], v[208:211], v[22:25]
	v_mfma_f32_16x16x32_bf16 v[14:17], v[164:167], v[208:211], v[14:17]
	s_setprio 0
	s_barrier
	s_add_u32 s26, s26, 0x80080
	s_addc_u32 s27, s27, 0
	s_add_i32 s44, s44, s6
	s_mov_b32 m0, s44
	s_nop 0
	global_load_lds_dwordx4 v0, s[26:27]
	s_add_i32 m0, s44, 0x2000
	s_nop 0
	global_load_lds_dwordx4 v138, s[26:27]
	s_waitcnt vmcnt(6)
	s_barrier
	s_setprio 1
	v_mfma_f32_16x16x32_bf16 v[50:53], v[212:215], v[180:183], v[50:53]
	v_mfma_f32_16x16x32_bf16 v[42:45], v[220:223], v[180:183], v[42:45]
	v_mfma_f32_16x16x32_bf16 v[34:37], v[212:215], v[188:191], v[34:37]
	v_mfma_f32_16x16x32_bf16 v[26:29], v[220:223], v[188:191], v[26:29]
	v_mfma_f32_16x16x32_bf16 v[18:21], v[212:215], v[196:199], v[18:21]
	v_mfma_f32_16x16x32_bf16 v[10:13], v[220:223], v[196:199], v[10:13]
	v_mfma_f32_16x16x32_bf16 v[6:9], v[212:215], v[204:207], v[6:9]
	v_mfma_f32_16x16x32_bf16 v[2:5], v[220:223], v[204:207], v[2:5]
	v_mfma_f32_16x16x32_bf16 v[50:53], v[216:219], v[184:187], v[50:53]
	v_mfma_f32_16x16x32_bf16 v[42:45], v[224:227], v[184:187], v[42:45]
	v_mfma_f32_16x16x32_bf16 v[34:37], v[216:219], v[192:195], v[34:37]
	v_mfma_f32_16x16x32_bf16 v[26:29], v[224:227], v[192:195], v[26:29]
	v_mfma_f32_16x16x32_bf16 v[18:21], v[216:219], v[200:203], v[18:21]
	v_mfma_f32_16x16x32_bf16 v[10:13], v[224:227], v[200:203], v[10:13]
	v_mfma_f32_16x16x32_bf16 v[6:9], v[216:219], v[208:211], v[6:9]
	v_mfma_f32_16x16x32_bf16 v[2:5], v[224:227], v[208:211], v[2:5]
	s_setprio 0
	s_add_i32 s57, s57, 2
	s_add_u32 s42, s42, 0x100
	s_addc_u32 s43, s43, 0
	s_add_u32 s55, s55, 0x100
	s_addc_u32 s56, s56, 0
	s_cmp_gt_u32 s57, 29
	s_barrier
	s_cbranch_scc0 .LBB0_627
	v_lshl_or_b32 v134, s51, 8, v154
	v_lshl_add_u32 v158, s52, 8, v152
	v_ashrrev_i32_e32 v135, 31, v134
	v_mov_b64_e32 v[148:149], s[88:89]
	s_movk_i32 s1, 0x2200
	v_mad_i64_i32 v[156:157], s[26:27], v158, s1, v[148:149]
	v_lshlrev_b64 v[150:151], 1, v[134:135]
	v_lshl_add_u64 v[134:135], v[156:157], 0, v[150:151]
	v_cvt_pk_bf16_f32 v126, v126, v127
	v_cvt_pk_bf16_f32 v127, v128, v129
	v_cvt_pk_bf16_f32 v128, v122, v123
	v_cvt_pk_bf16_f32 v129, v124, v125
	global_store_dwordx4 v[134:135], v[126:129], off
	v_cvt_pk_bf16_f32 v114, v114, v115
	v_cvt_pk_bf16_f32 v115, v116, v117
	v_cvt_pk_bf16_f32 v116, v106, v107
	v_or_b32_e32 v106, 16, v158
	v_mad_i64_i32 v[106:107], s[26:27], v106, s1, v[148:149]
	v_cvt_pk_bf16_f32 v117, v108, v109
	global_store_dwordx4 v[134:135], v[114:117], off offset:256
	s_and_b64 vcc, exec, s[40:41]
	s_mov_b32 s51, s0
	v_lshl_add_u64 v[114:115], v[106:107], 0, v[150:151]
	v_cvt_pk_bf16_f32 v106, v118, v119
	v_cvt_pk_bf16_f32 v107, v120, v121
	v_cvt_pk_bf16_f32 v108, v110, v111
	v_cvt_pk_bf16_f32 v109, v112, v113
	global_store_dwordx4 v[114:115], v[106:109], off
	v_cvt_pk_bf16_f32 v98, v98, v99
	v_cvt_pk_bf16_f32 v99, v100, v101
	v_cvt_pk_bf16_f32 v100, v90, v91
	v_or_b32_e32 v90, 32, v158
	v_mad_i64_i32 v[90:91], s[26:27], v90, s1, v[148:149]
	v_cvt_pk_bf16_f32 v101, v92, v93
	global_store_dwordx4 v[114:115], v[98:101], off offset:256
	s_mov_b32 s52, s22
	s_mov_b64 s[42:43], s[24:25]
	v_lshl_add_u64 v[98:99], v[90:91], 0, v[150:151]
	v_cvt_pk_bf16_f32 v90, v102, v103
	v_cvt_pk_bf16_f32 v91, v104, v105
	v_cvt_pk_bf16_f32 v92, v94, v95
	v_cvt_pk_bf16_f32 v93, v96, v97
	global_store_dwordx4 v[98:99], v[90:93], off
	v_cvt_pk_bf16_f32 v82, v82, v83
	v_cvt_pk_bf16_f32 v83, v84, v85
	v_cvt_pk_bf16_f32 v84, v74, v75
	v_or_b32_e32 v74, 48, v158
	v_mad_i64_i32 v[74:75], s[26:27], v74, s1, v[148:149]
	v_cvt_pk_bf16_f32 v85, v76, v77
	global_store_dwordx4 v[98:99], v[82:85], off offset:256
	s_nop 1
	v_lshl_add_u64 v[82:83], v[74:75], 0, v[150:151]
	v_cvt_pk_bf16_f32 v74, v86, v87
	v_cvt_pk_bf16_f32 v75, v88, v89
	v_cvt_pk_bf16_f32 v76, v78, v79
	v_cvt_pk_bf16_f32 v77, v80, v81
	global_store_dwordx4 v[82:83], v[74:77], off
	v_cvt_pk_bf16_f32 v70, v70, v71
	v_cvt_pk_bf16_f32 v71, v72, v73
	v_cvt_pk_bf16_f32 v72, v66, v67
	v_add_u32_e32 v66, 0x80, v158
	v_mad_i64_i32 v[66:67], s[26:27], v66, s1, v[148:149]
	v_lshl_add_u64 v[66:67], v[66:67], 0, v[150:151]
	v_cvt_pk_bf16_f32 v73, v68, v69
	global_store_dwordx4 v[82:83], v[70:73], off offset:256
	v_cvt_pk_bf16_f32 v62, v62, v63
	v_cvt_pk_bf16_f32 v63, v64, v65
	v_cvt_pk_bf16_f32 v64, v58, v59
	v_cvt_pk_bf16_f32 v65, v60, v61
	global_store_dwordx4 v[66:67], v[62:65], off
	v_cvt_pk_bf16_f32 v50, v50, v51
	v_cvt_pk_bf16_f32 v51, v52, v53
	v_cvt_pk_bf16_f32 v52, v42, v43
	v_add_u32_e32 v42, 0x90, v158
	v_mad_i64_i32 v[42:43], s[26:27], v42, s1, v[148:149]
	v_cvt_pk_bf16_f32 v53, v44, v45
	global_store_dwordx4 v[66:67], v[50:53], off offset:256
	s_nop 1
	v_lshl_add_u64 v[50:51], v[42:43], 0, v[150:151]
	v_cvt_pk_bf16_f32 v42, v54, v55
	v_cvt_pk_bf16_f32 v43, v56, v57
	v_cvt_pk_bf16_f32 v44, v46, v47
	v_cvt_pk_bf16_f32 v45, v48, v49
	global_store_dwordx4 v[50:51], v[42:45], off
	v_cvt_pk_bf16_f32 v34, v34, v35
	v_cvt_pk_bf16_f32 v35, v36, v37
	v_cvt_pk_bf16_f32 v36, v26, v27
	v_add_u32_e32 v26, 0xa0, v158
	v_mad_i64_i32 v[26:27], s[26:27], v26, s1, v[148:149]
	v_cvt_pk_bf16_f32 v37, v28, v29
	global_store_dwordx4 v[50:51], v[34:37], off offset:256
	s_nop 1
	v_lshl_add_u64 v[34:35], v[26:27], 0, v[150:151]
	v_cvt_pk_bf16_f32 v26, v38, v39
	v_cvt_pk_bf16_f32 v27, v40, v41
	v_cvt_pk_bf16_f32 v28, v30, v31
	v_cvt_pk_bf16_f32 v29, v32, v33
	global_store_dwordx4 v[34:35], v[26:29], off
	v_cvt_pk_bf16_f32 v18, v18, v19
	v_cvt_pk_bf16_f32 v19, v20, v21
	v_cvt_pk_bf16_f32 v20, v10, v11
	v_add_u32_e32 v10, 0xb0, v158
	v_mad_i64_i32 v[10:11], s[26:27], v10, s1, v[148:149]
	v_cvt_pk_bf16_f32 v21, v12, v13
	global_store_dwordx4 v[34:35], v[18:21], off offset:256
	s_mov_b64 s[26:27], s[38:39]
	s_nop 0
	v_lshl_add_u64 v[18:19], v[10:11], 0, v[150:151]
	v_cvt_pk_bf16_f32 v10, v22, v23
	v_cvt_pk_bf16_f32 v11, v24, v25
	v_cvt_pk_bf16_f32 v12, v14, v15
	v_cvt_pk_bf16_f32 v13, v16, v17
	global_store_dwordx4 v[18:19], v[10:13], off
	v_cvt_pk_bf16_f32 v6, v6, v7
	v_cvt_pk_bf16_f32 v7, v8, v9
	v_cvt_pk_bf16_f32 v8, v2, v3
	v_cvt_pk_bf16_f32 v9, v4, v5
	global_store_dwordx4 v[18:19], v[6:9], off offset:256
	s_cbranch_vccz .LBB0_624
	s_waitcnt vmcnt(0)
	v_readlane_b32 s52, v254, 26
	v_readlane_b32 s50, v254, 28
	s_cmpk_gt_u32 s4, 0xff
	v_readlane_b32 s53, v254, 27
	v_readlane_b32 s51, v254, 29
	s_cbranch_scc1 .LBB0_631
	s_barrier

.LBB0_1034:
	s_add_u32 s26, s42, 0xfff80080
	s_addc_u32 s27, s43, -1
	s_add_i32 s58, 0, 0x10000
	v_add_u32_e32 v134, s58, v155
	ds_read_b128 v[148:151], v134
	ds_read_b128 v[158:161], v134 offset:1024
	ds_read_b128 v[162:165], v134 offset:2048
	ds_read_b128 v[180:183], v134 offset:3072
	s_cmp_eq_u32 s57, 28
	s_cselect_b32 s45, s23, s27
	s_cselect_b32 s44, s53, s26
	s_cselect_b32 s27, s1, s56
	s_cselect_b32 s26, s54, s55
	s_add_i32 m0, s7, 0xc000
	ds_read_b128 v[184:187], v157
	ds_read_b128 v[188:191], v157 offset:1024
	ds_read_b128 v[192:195], v157 offset:2048
	ds_read_b128 v[196:199], v157 offset:3072
	ds_read_b128 v[200:203], v157 offset:4096
	ds_read_b128 v[204:207], v157 offset:5120
	ds_read_b128 v[208:211], v157 offset:6144
	ds_read_b128 v[212:215], v157 offset:7168
	global_load_lds_dwordx4 v144, s[42:43]
	s_add_i32 m0, s7, 0xe000
	s_nop 0
	global_load_lds_dwordx4 v146, s[42:43]
	s_waitcnt lgkmcnt(8)
	s_barrier
	s_waitcnt lgkmcnt(0)
	s_setprio 1
	s_waitcnt lgkmcnt(0)
	v_mfma_f32_16x16x32_bf16 v[126:129], v[148:151], v[184:187], v[126:129]
	v_mfma_f32_16x16x32_bf16 v[122:125], v[162:165], v[184:187], v[122:125]
	v_mfma_f32_16x16x32_bf16 v[110:113], v[148:151], v[192:195], v[110:113]
	v_mfma_f32_16x16x32_bf16 v[106:109], v[162:165], v[192:195], v[106:109]
	v_mfma_f32_16x16x32_bf16 v[94:97], v[148:151], v[200:203], v[94:97]
	v_mfma_f32_16x16x32_bf16 v[90:93], v[162:165], v[200:203], v[90:93]
	v_mfma_f32_16x16x32_bf16 v[78:81], v[148:151], v[208:211], v[78:81]
	v_mfma_f32_16x16x32_bf16 v[74:77], v[162:165], v[208:211], v[74:77]
	v_mfma_f32_16x16x32_bf16 v[126:129], v[158:161], v[188:191], v[126:129]
	v_mfma_f32_16x16x32_bf16 v[122:125], v[180:183], v[188:191], v[122:125]
	v_mfma_f32_16x16x32_bf16 v[110:113], v[158:161], v[196:199], v[110:113]
	v_mfma_f32_16x16x32_bf16 v[106:109], v[180:183], v[196:199], v[106:109]
	v_mfma_f32_16x16x32_bf16 v[94:97], v[158:161], v[204:207], v[94:97]
	v_mfma_f32_16x16x32_bf16 v[90:93], v[180:183], v[204:207], v[90:93]
	v_mfma_f32_16x16x32_bf16 v[78:81], v[158:161], v[212:215], v[78:81]
	v_mfma_f32_16x16x32_bf16 v[74:77], v[180:183], v[212:215], v[74:77]
	s_setprio 0
	s_barrier
	s_add_i32 s60, 0, 0x14000
	s_add_i32 s58, s58, s6
	ds_read_b128 v[216:219], v134 offset:16384
	ds_read_b128 v[220:223], v134 offset:17408
	ds_read_b128 v[224:227], v134 offset:18432
	ds_read_b128 v[228:231], v134 offset:19456
	s_mov_b32 m0, s58
	global_load_lds_dwordx4 v0, s[26:27]
	s_add_i32 m0, s58, 0x2000
	s_nop 0
	global_load_lds_dwordx4 v138, s[26:27]
	s_barrier
	s_waitcnt lgkmcnt(0)
	s_setprio 1
	s_waitcnt lgkmcnt(0)
	v_mfma_f32_16x16x32_bf16 v[118:121], v[216:219], v[184:187], v[118:121]
	v_mfma_f32_16x16x32_bf16 v[114:117], v[224:227], v[184:187], v[114:117]
	v_mfma_f32_16x16x32_bf16 v[102:105], v[216:219], v[192:195], v[102:105]
	v_mfma_f32_16x16x32_bf16 v[98:101], v[224:227], v[192:195], v[98:101]
	v_mfma_f32_16x16x32_bf16 v[86:89], v[216:219], v[200:203], v[86:89]
	v_mfma_f32_16x16x32_bf16 v[82:85], v[224:227], v[200:203], v[82:85]
	v_mfma_f32_16x16x32_bf16 v[70:73], v[216:219], v[208:211], v[70:73]
	v_mfma_f32_16x16x32_bf16 v[66:69], v[224:227], v[208:211], v[66:69]
	v_mfma_f32_16x16x32_bf16 v[118:121], v[220:223], v[188:191], v[118:121]
	v_mfma_f32_16x16x32_bf16 v[114:117], v[228:231], v[188:191], v[114:117]
	v_mfma_f32_16x16x32_bf16 v[102:105], v[220:223], v[196:199], v[102:105]
	v_mfma_f32_16x16x32_bf16 v[98:101], v[228:231], v[196:199], v[98:101]
	v_mfma_f32_16x16x32_bf16 v[86:89], v[220:223], v[204:207], v[86:89]
	v_mfma_f32_16x16x32_bf16 v[82:85], v[228:231], v[204:207], v[82:85]
	v_mfma_f32_16x16x32_bf16 v[70:73], v[220:223], v[212:215], v[70:73]
	v_mfma_f32_16x16x32_bf16 v[66:69], v[228:231], v[212:215], v[66:69]
	s_setprio 0
	s_mov_b32 m0, s7
	s_add_u32 vcc_lo, s44, s10
	s_addc_u32 vcc_hi, s45, s11
	s_barrier
	ds_read_b128 v[184:187], v157 offset:16384
	ds_read_b128 v[188:191], v157 offset:17408
	ds_read_b128 v[192:195], v157 offset:18432
	ds_read_b128 v[196:199], v157 offset:19456
	ds_read_b128 v[200:203], v157 offset:20480
	ds_read_b128 v[204:207], v157 offset:21504
	ds_read_b128 v[208:211], v157 offset:22528
	ds_read_b128 v[212:215], v157 offset:23552
	global_load_lds_dwordx4 v142, s[44:45]
	s_mov_b32 m0, s14
	s_nop 0
	global_load_lds_dwordx4 v140, s[44:45]
	s_barrier
	s_waitcnt lgkmcnt(0)
	s_setprio 1
	s_waitcnt lgkmcnt(0)
	v_mfma_f32_16x16x32_bf16 v[62:65], v[148:151], v[184:187], v[62:65]
	v_mfma_f32_16x16x32_bf16 v[58:61], v[162:165], v[184:187], v[58:61]
	v_mfma_f32_16x16x32_bf16 v[46:49], v[148:151], v[192:195], v[46:49]
	v_mfma_f32_16x16x32_bf16 v[42:45], v[162:165], v[192:195], v[42:45]
	v_mfma_f32_16x16x32_bf16 v[30:33], v[148:151], v[200:203], v[30:33]
	v_mfma_f32_16x16x32_bf16 v[26:29], v[162:165], v[200:203], v[26:29]
	v_mfma_f32_16x16x32_bf16 v[14:17], v[148:151], v[208:211], v[14:17]
	v_mfma_f32_16x16x32_bf16 v[10:13], v[162:165], v[208:211], v[10:13]
	v_mfma_f32_16x16x32_bf16 v[62:65], v[158:161], v[188:191], v[62:65]
	v_mfma_f32_16x16x32_bf16 v[58:61], v[180:183], v[188:191], v[58:61]
	v_mfma_f32_16x16x32_bf16 v[46:49], v[158:161], v[196:199], v[46:49]
	v_mfma_f32_16x16x32_bf16 v[42:45], v[180:183], v[196:199], v[42:45]
	v_mfma_f32_16x16x32_bf16 v[30:33], v[158:161], v[204:207], v[30:33]
	v_mfma_f32_16x16x32_bf16 v[26:29], v[180:183], v[204:207], v[26:29]
	v_mfma_f32_16x16x32_bf16 v[14:17], v[158:161], v[212:215], v[14:17]
	v_mfma_f32_16x16x32_bf16 v[10:13], v[180:183], v[212:215], v[10:13]
	s_setprio 0
	s_barrier
	s_add_u32 s58, s26, 0x80000
	s_addc_u32 s59, s27, 0
	s_add_i32 s60, s60, s6
	s_mov_b32 m0, s60
	s_nop 0
	global_load_lds_dwordx4 v0, s[58:59]
	s_add_i32 m0, s60, 0x2000
	s_nop 0
	global_load_lds_dwordx4 v138, s[58:59]
	s_waitcnt vmcnt(6)
	s_barrier
	s_setprio 1
	v_mfma_f32_16x16x32_bf16 v[54:57], v[216:219], v[184:187], v[54:57]
	v_mfma_f32_16x16x32_bf16 v[50:53], v[224:227], v[184:187], v[50:53]
	v_mfma_f32_16x16x32_bf16 v[38:41], v[216:219], v[192:195], v[38:41]
	v_mfma_f32_16x16x32_bf16 v[34:37], v[224:227], v[192:195], v[34:37]
	v_mfma_f32_16x16x32_bf16 v[22:25], v[216:219], v[200:203], v[22:25]
	v_mfma_f32_16x16x32_bf16 v[18:21], v[224:227], v[200:203], v[18:21]
	v_mfma_f32_16x16x32_bf16 v[6:9], v[216:219], v[208:211], v[6:9]
	v_mfma_f32_16x16x32_bf16 v[2:5], v[224:227], v[208:211], v[2:5]
	v_mfma_f32_16x16x32_bf16 v[54:57], v[220:223], v[188:191], v[54:57]
	v_mfma_f32_16x16x32_bf16 v[50:53], v[228:231], v[188:191], v[50:53]
	v_mfma_f32_16x16x32_bf16 v[38:41], v[220:223], v[196:199], v[38:41]
	v_mfma_f32_16x16x32_bf16 v[34:37], v[228:231], v[196:199], v[34:37]
	v_mfma_f32_16x16x32_bf16 v[22:25], v[220:223], v[204:207], v[22:25]
	v_mfma_f32_16x16x32_bf16 v[18:21], v[228:231], v[204:207], v[18:21]
	v_mfma_f32_16x16x32_bf16 v[6:9], v[220:223], v[212:215], v[6:9]
	v_mfma_f32_16x16x32_bf16 v[2:5], v[228:231], v[212:215], v[2:5]
	s_setprio 0
	s_add_i32 s58, 0, 0x18000
	s_barrier
	ds_read_b128 v[148:151], v134 offset:32768
	ds_read_b128 v[158:161], v134 offset:33792
	ds_read_b128 v[162:165], v134 offset:34816
	ds_read_b128 v[180:183], v134 offset:35840
	s_add_u32 s44, s44, 0x80000
	s_addc_u32 s45, s45, 0
	s_mov_b32 m0, s46
	ds_read_b128 v[184:187], v157 offset:32768
	ds_read_b128 v[188:191], v157 offset:33792
	ds_read_b128 v[192:195], v157 offset:34816
	ds_read_b128 v[196:199], v157 offset:35840
	ds_read_b128 v[200:203], v157 offset:36864
	ds_read_b128 v[204:207], v157 offset:37888
	ds_read_b128 v[208:211], v157 offset:38912
	ds_read_b128 v[212:215], v157 offset:39936
	global_load_lds_dwordx4 v142, s[44:45]
	s_mov_b32 m0, s47
	s_nop 0
	global_load_lds_dwordx4 v140, s[44:45]
	s_waitcnt lgkmcnt(8)
	s_barrier
	s_waitcnt lgkmcnt(0)
	s_setprio 1
	s_waitcnt lgkmcnt(0)
	v_mfma_f32_16x16x32_bf16 v[126:129], v[148:151], v[184:187], v[126:129]
	v_mfma_f32_16x16x32_bf16 v[122:125], v[162:165], v[184:187], v[122:125]
	v_mfma_f32_16x16x32_bf16 v[110:113], v[148:151], v[192:195], v[110:113]
	v_mfma_f32_16x16x32_bf16 v[106:109], v[162:165], v[192:195], v[106:109]
	v_mfma_f32_16x16x32_bf16 v[94:97], v[148:151], v[200:203], v[94:97]
	v_mfma_f32_16x16x32_bf16 v[90:93], v[162:165], v[200:203], v[90:93]
	v_mfma_f32_16x16x32_bf16 v[78:81], v[148:151], v[208:211], v[78:81]
	v_mfma_f32_16x16x32_bf16 v[74:77], v[162:165], v[208:211], v[74:77]
	v_mfma_f32_16x16x32_bf16 v[126:129], v[158:161], v[188:191], v[126:129]
	v_mfma_f32_16x16x32_bf16 v[122:125], v[180:183], v[188:191], v[122:125]
	v_mfma_f32_16x16x32_bf16 v[110:113], v[158:161], v[196:199], v[110:113]
	v_mfma_f32_16x16x32_bf16 v[106:109], v[180:183], v[196:199], v[106:109]
	v_mfma_f32_16x16x32_bf16 v[94:97], v[158:161], v[204:207], v[94:97]
	v_mfma_f32_16x16x32_bf16 v[90:93], v[180:183], v[204:207], v[90:93]
	v_mfma_f32_16x16x32_bf16 v[78:81], v[158:161], v[212:215], v[78:81]
	v_mfma_f32_16x16x32_bf16 v[74:77], v[180:183], v[212:215], v[74:77]
	s_setprio 0
	s_barrier
	s_add_i32 s44, 0, 0x1c000
	s_add_i32 s45, s58, s6
	s_add_u32 s100, s26, s10
	s_addc_u32 s101, s27, s11
	s_mov_b32 m0, s45
	ds_read_b128 v[216:219], v134 offset:49152
	ds_read_b128 v[220:223], v134 offset:50176
	ds_read_b128 v[224:227], v134 offset:51200
	ds_read_b128 v[228:231], v134 offset:52224
	global_load_lds_dwordx4 v0, s[100:101]
	s_add_u32 s100, s26, s10
	s_addc_u32 s101, s27, s11
	s_add_i32 m0, s45, 0x2000
	s_nop 0
	global_load_lds_dwordx4 v138, s[100:101]
	s_barrier
	s_waitcnt lgkmcnt(0)
	s_setprio 1
	s_waitcnt lgkmcnt(0)
	v_mfma_f32_16x16x32_bf16 v[118:121], v[216:219], v[184:187], v[118:121]
	v_mfma_f32_16x16x32_bf16 v[114:117], v[224:227], v[184:187], v[114:117]
	v_mfma_f32_16x16x32_bf16 v[102:105], v[216:219], v[192:195], v[102:105]
	v_mfma_f32_16x16x32_bf16 v[98:101], v[224:227], v[192:195], v[98:101]
	v_mfma_f32_16x16x32_bf16 v[86:89], v[216:219], v[200:203], v[86:89]
	v_mfma_f32_16x16x32_bf16 v[82:85], v[224:227], v[200:203], v[82:85]
	v_mfma_f32_16x16x32_bf16 v[70:73], v[216:219], v[208:211], v[70:73]
	v_mfma_f32_16x16x32_bf16 v[66:69], v[224:227], v[208:211], v[66:69]
	v_mfma_f32_16x16x32_bf16 v[118:121], v[220:223], v[188:191], v[118:121]
	v_mfma_f32_16x16x32_bf16 v[114:117], v[228:231], v[188:191], v[114:117]
	v_mfma_f32_16x16x32_bf16 v[102:105], v[220:223], v[196:199], v[102:105]
	v_mfma_f32_16x16x32_bf16 v[98:101], v[228:231], v[196:199], v[98:101]
	v_mfma_f32_16x16x32_bf16 v[86:89], v[220:223], v[204:207], v[86:89]
	v_mfma_f32_16x16x32_bf16 v[82:85], v[228:231], v[204:207], v[82:85]
	v_mfma_f32_16x16x32_bf16 v[70:73], v[220:223], v[212:215], v[70:73]
	v_mfma_f32_16x16x32_bf16 v[66:69], v[228:231], v[212:215], v[66:69]
	s_setprio 0
	s_mov_b32 m0, s48
	s_barrier
	ds_read_b128 v[184:187], v157 offset:49152
	ds_read_b128 v[188:191], v157 offset:50176
	ds_read_b128 v[192:195], v157 offset:51200
	ds_read_b128 v[196:199], v157 offset:52224
	ds_read_b128 v[200:203], v157 offset:53248
	ds_read_b128 v[204:207], v157 offset:54272
	ds_read_b128 v[208:211], v157 offset:55296
	ds_read_b128 v[212:215], v157 offset:56320
	global_load_lds_dwordx4 v142, vcc
	s_mov_b32 m0, s49
	s_nop 0
	global_load_lds_dwordx4 v140, vcc
	s_barrier
	s_waitcnt lgkmcnt(0)
	s_setprio 1
	s_waitcnt lgkmcnt(0)
	v_mfma_f32_16x16x32_bf16 v[62:65], v[148:151], v[184:187], v[62:65]
	v_mfma_f32_16x16x32_bf16 v[58:61], v[162:165], v[184:187], v[58:61]
	v_mfma_f32_16x16x32_bf16 v[46:49], v[148:151], v[192:195], v[46:49]
	v_mfma_f32_16x16x32_bf16 v[42:45], v[162:165], v[192:195], v[42:45]
	v_mfma_f32_16x16x32_bf16 v[30:33], v[148:151], v[200:203], v[30:33]
	v_mfma_f32_16x16x32_bf16 v[26:29], v[162:165], v[200:203], v[26:29]
	v_mfma_f32_16x16x32_bf16 v[14:17], v[148:151], v[208:211], v[14:17]
	v_mfma_f32_16x16x32_bf16 v[10:13], v[162:165], v[208:211], v[10:13]
	v_mfma_f32_16x16x32_bf16 v[62:65], v[158:161], v[188:191], v[62:65]
	v_mfma_f32_16x16x32_bf16 v[58:61], v[180:183], v[188:191], v[58:61]
	v_mfma_f32_16x16x32_bf16 v[46:49], v[158:161], v[196:199], v[46:49]
	v_mfma_f32_16x16x32_bf16 v[42:45], v[180:183], v[196:199], v[42:45]
	v_mfma_f32_16x16x32_bf16 v[30:33], v[158:161], v[204:207], v[30:33]
	v_mfma_f32_16x16x32_bf16 v[26:29], v[180:183], v[204:207], v[26:29]
	v_mfma_f32_16x16x32_bf16 v[14:17], v[158:161], v[212:215], v[14:17]
	v_mfma_f32_16x16x32_bf16 v[10:13], v[180:183], v[212:215], v[10:13]
	s_setprio 0
	s_barrier
	s_add_u32 s26, s26, 0x80080
	s_addc_u32 s27, s27, 0
	s_add_i32 s44, s44, s6
	s_mov_b32 m0, s44
	s_nop 0
	global_load_lds_dwordx4 v0, s[26:27]
	s_add_i32 m0, s44, 0x2000
	s_nop 0
	global_load_lds_dwordx4 v138, s[26:27]
	s_waitcnt vmcnt(6)
	s_barrier
	s_setprio 1
	v_mfma_f32_16x16x32_bf16 v[54:57], v[216:219], v[184:187], v[54:57]
	v_mfma_f32_16x16x32_bf16 v[50:53], v[224:227], v[184:187], v[50:53]
	v_mfma_f32_16x16x32_bf16 v[38:41], v[216:219], v[192:195], v[38:41]
	v_mfma_f32_16x16x32_bf16 v[34:37], v[224:227], v[192:195], v[34:37]
	v_mfma_f32_16x16x32_bf16 v[22:25], v[216:219], v[200:203], v[22:25]
	v_mfma_f32_16x16x32_bf16 v[18:21], v[224:227], v[200:203], v[18:21]
	v_mfma_f32_16x16x32_bf16 v[6:9], v[216:219], v[208:211], v[6:9]
	v_mfma_f32_16x16x32_bf16 v[2:5], v[224:227], v[208:211], v[2:5]
	v_mfma_f32_16x16x32_bf16 v[54:57], v[220:223], v[188:191], v[54:57]
	v_mfma_f32_16x16x32_bf16 v[50:53], v[228:231], v[188:191], v[50:53]
	v_mfma_f32_16x16x32_bf16 v[38:41], v[220:223], v[196:199], v[38:41]
	v_mfma_f32_16x16x32_bf16 v[34:37], v[228:231], v[196:199], v[34:37]
	v_mfma_f32_16x16x32_bf16 v[22:25], v[220:223], v[204:207], v[22:25]
	v_mfma_f32_16x16x32_bf16 v[18:21], v[228:231], v[204:207], v[18:21]
	v_mfma_f32_16x16x32_bf16 v[6:9], v[220:223], v[212:215], v[6:9]
	v_mfma_f32_16x16x32_bf16 v[2:5], v[228:231], v[212:215], v[2:5]
	s_setprio 0
	s_add_i32 s57, s57, 2
	s_add_u32 s42, s42, 0x100
	s_addc_u32 s43, s43, 0
	s_add_u32 s55, s55, 0x100
	s_addc_u32 s56, s56, 0
	s_cmp_gt_u32 s57, 29
	s_barrier
	s_cbranch_scc0 .LBB0_1034
	v_lshl_add_u32 v150, s52, 8, v154
	v_lshl_or_b32 v134, s51, 8, v156
	v_ashrrev_i32_e32 v151, 31, v150
	v_ashrrev_i32_e32 v135, 31, v134
	v_lshlrev_b64 v[148:149], 13, v[150:151]
	v_lshl_add_u64 v[148:149], s[76:77], 0, v[148:149]
	v_lshlrev_b64 v[152:153], 2, v[134:135]
	v_lshl_add_u64 v[158:159], v[148:149], 0, v[152:153]
	v_readlane_b32 s56, v254, 30
	v_readlane_b32 s54, v254, 32
	v_readlane_b32 s60, v254, 39
	s_mov_b32 s51, s0
	s_mov_b32 s52, s22
	s_mov_b64 s[42:43], s[24:25]
	v_readlane_b32 s57, v254, 31
	v_readlane_b32 s55, v254, 33
	v_readlane_b32 s44, v254, 46
	v_readlane_b32 s61, v254, 40
	v_readlane_b32 s45, v254, 47
	v_mov_b64_e32 v[162:163], v[158:159]
	global_load_dwordx4 v[180:183], v[162:163], off
	global_load_dwordx4 v[184:187], v[162:163], off offset:16
	global_load_dwordx4 v[188:191], v[162:163], off offset:512
	global_load_dwordx4 v[192:195], v[162:163], off offset:528
	s_mov_b64 s[26:27], 0x20000
	v_lshl_add_u64 v[164:165], v[158:159], 0, s[26:27]
	global_load_dwordx4 v[196:199], v[164:165], off
	global_load_dwordx4 v[200:203], v[164:165], off offset:16
	global_load_dwordx4 v[204:207], v[164:165], off offset:512
	global_load_dwordx4 v[208:211], v[164:165], off offset:528
	s_mov_b64 s[26:27], 0x40000
	v_lshl_add_u64 v[150:151], v[158:159], 0, s[26:27]
	global_load_dwordx4 v[212:215], v[150:151], off
	global_load_dwordx4 v[216:219], v[150:151], off offset:16
	global_load_dwordx4 v[220:223], v[150:151], off offset:512
	global_load_dwordx4 v[224:227], v[150:151], off offset:528
	s_waitcnt vmcnt(8)
	v_pk_add_f32 v[126:127], v[126:127], v[180:181]
	v_pk_add_f32 v[128:129], v[128:129], v[182:183]
	v_pk_add_f32 v[122:123], v[122:123], v[184:185]
	v_pk_add_f32 v[124:125], v[124:125], v[186:187]
	v_pk_add_f32 v[118:119], v[118:119], v[188:189]
	v_pk_add_f32 v[120:121], v[120:121], v[190:191]
	v_pk_add_f32 v[114:115], v[114:115], v[192:193]
	v_pk_add_f32 v[116:117], v[116:117], v[194:195]
	global_store_dwordx4 v[162:163], v[126:129], off
	global_store_dwordx4 v[162:163], v[122:125], off offset:16
	global_store_dwordx4 v[162:163], v[118:121], off offset:512
	global_store_dwordx4 v[162:163], v[114:117], off offset:528
	s_mov_b64 s[26:27], 0x60000
	v_lshl_add_u64 v[228:229], v[158:159], 0, s[26:27]
	global_load_dwordx4 v[180:183], v[228:229], off
	global_load_dwordx4 v[184:187], v[228:229], off offset:16
	global_load_dwordx4 v[188:191], v[228:229], off offset:512
	global_load_dwordx4 v[192:195], v[228:229], off offset:528
	s_waitcnt vmcnt(12)
	v_pk_add_f32 v[110:111], v[110:111], v[196:197]
	v_pk_add_f32 v[112:113], v[112:113], v[198:199]
	v_pk_add_f32 v[106:107], v[106:107], v[200:201]
	v_pk_add_f32 v[108:109], v[108:109], v[202:203]
	v_pk_add_f32 v[102:103], v[102:103], v[204:205]
	v_pk_add_f32 v[104:105], v[104:105], v[206:207]
	v_pk_add_f32 v[98:99], v[98:99], v[208:209]
	v_pk_add_f32 v[100:101], v[100:101], v[210:211]
	global_store_dwordx4 v[164:165], v[110:113], off
	global_store_dwordx4 v[164:165], v[106:109], off offset:16
	global_store_dwordx4 v[164:165], v[102:105], off offset:512
	global_store_dwordx4 v[164:165], v[98:101], off offset:528
	s_mov_b64 s[26:27], 0x100000
	v_lshl_add_u64 v[162:163], v[158:159], 0, s[26:27]
	global_load_dwordx4 v[196:199], v[162:163], off
	global_load_dwordx4 v[200:203], v[162:163], off offset:16
	global_load_dwordx4 v[204:207], v[162:163], off offset:512
	global_load_dwordx4 v[208:211], v[162:163], off offset:528
	s_waitcnt vmcnt(16)
	v_pk_add_f32 v[94:95], v[94:95], v[212:213]
	v_pk_add_f32 v[96:97], v[96:97], v[214:215]
	v_pk_add_f32 v[90:91], v[90:91], v[216:217]
	v_pk_add_f32 v[92:93], v[92:93], v[218:219]
	v_pk_add_f32 v[86:87], v[86:87], v[220:221]
	v_pk_add_f32 v[88:89], v[88:89], v[222:223]
	v_pk_add_f32 v[82:83], v[82:83], v[224:225]
	v_pk_add_f32 v[84:85], v[84:85], v[226:227]
	global_store_dwordx4 v[150:151], v[94:97], off
	global_store_dwordx4 v[150:151], v[90:93], off offset:16
	global_store_dwordx4 v[150:151], v[86:89], off offset:512
	global_store_dwordx4 v[150:151], v[82:85], off offset:528
	s_mov_b64 s[26:27], 0x120000
	v_lshl_add_u64 v[164:165], v[158:159], 0, s[26:27]
	global_load_dwordx4 v[212:215], v[164:165], off
	global_load_dwordx4 v[216:219], v[164:165], off offset:16
	global_load_dwordx4 v[220:223], v[164:165], off offset:512
	global_load_dwordx4 v[224:227], v[164:165], off offset:528
	s_waitcnt vmcnt(16)
	v_pk_add_f32 v[78:79], v[78:79], v[180:181]
	v_pk_add_f32 v[80:81], v[80:81], v[182:183]
	v_pk_add_f32 v[74:75], v[74:75], v[184:185]
	v_pk_add_f32 v[76:77], v[76:77], v[186:187]
	v_pk_add_f32 v[70:71], v[70:71], v[188:189]
	v_pk_add_f32 v[72:73], v[72:73], v[190:191]
	v_pk_add_f32 v[66:67], v[66:67], v[192:193]
	v_pk_add_f32 v[68:69], v[68:69], v[194:195]
	global_store_dwordx4 v[228:229], v[78:81], off
	global_store_dwordx4 v[228:229], v[74:77], off offset:16
	global_store_dwordx4 v[228:229], v[70:73], off offset:512
	global_store_dwordx4 v[228:229], v[66:69], off offset:528
	s_mov_b64 s[26:27], 0x140000
	v_lshl_add_u64 v[150:151], v[158:159], 0, s[26:27]
	global_load_dwordx4 v[180:183], v[150:151], off
	global_load_dwordx4 v[184:187], v[150:151], off offset:16
	global_load_dwordx4 v[188:191], v[150:151], off offset:512
	global_load_dwordx4 v[192:195], v[150:151], off offset:528
	s_waitcnt vmcnt(16)
	v_pk_add_f32 v[62:63], v[62:63], v[196:197]
	v_pk_add_f32 v[64:65], v[64:65], v[198:199]
	v_pk_add_f32 v[58:59], v[58:59], v[200:201]
	v_pk_add_f32 v[60:61], v[60:61], v[202:203]
	v_pk_add_f32 v[54:55], v[54:55], v[204:205]
	v_pk_add_f32 v[56:57], v[56:57], v[206:207]
	v_pk_add_f32 v[50:51], v[50:51], v[208:209]
	v_pk_add_f32 v[52:53], v[52:53], v[210:211]
	global_store_dwordx4 v[162:163], v[62:65], off
	global_store_dwordx4 v[162:163], v[58:61], off offset:16
	global_store_dwordx4 v[162:163], v[54:57], off offset:512
	global_store_dwordx4 v[162:163], v[50:53], off offset:528
	s_mov_b64 s[26:27], 0x160000
	v_lshl_add_u64 v[228:229], v[158:159], 0, s[26:27]
	global_load_dwordx4 v[196:199], v[228:229], off
	global_load_dwordx4 v[200:203], v[228:229], off offset:16
	global_load_dwordx4 v[204:207], v[228:229], off offset:512
	global_load_dwordx4 v[208:211], v[228:229], off offset:528
	s_waitcnt vmcnt(16)
	v_pk_add_f32 v[46:47], v[46:47], v[212:213]
	v_pk_add_f32 v[48:49], v[48:49], v[214:215]
	v_pk_add_f32 v[42:43], v[42:43], v[216:217]
	v_pk_add_f32 v[44:45], v[44:45], v[218:219]
	v_pk_add_f32 v[38:39], v[38:39], v[220:221]
	v_pk_add_f32 v[40:41], v[40:41], v[222:223]
	v_pk_add_f32 v[34:35], v[34:35], v[224:225]
	v_pk_add_f32 v[36:37], v[36:37], v[226:227]
	global_store_dwordx4 v[164:165], v[46:49], off
	global_store_dwordx4 v[164:165], v[42:45], off offset:16
	global_store_dwordx4 v[164:165], v[38:41], off offset:512
	global_store_dwordx4 v[164:165], v[34:37], off offset:528
	s_waitcnt vmcnt(12)
	v_pk_add_f32 v[30:31], v[30:31], v[180:181]
	v_pk_add_f32 v[32:33], v[32:33], v[182:183]
	v_pk_add_f32 v[26:27], v[26:27], v[184:185]
	v_pk_add_f32 v[28:29], v[28:29], v[186:187]
	v_pk_add_f32 v[22:23], v[22:23], v[188:189]
	v_pk_add_f32 v[24:25], v[24:25], v[190:191]
	v_pk_add_f32 v[18:19], v[18:19], v[192:193]
	v_pk_add_f32 v[20:21], v[20:21], v[194:195]
	global_store_dwordx4 v[150:151], v[30:33], off
	global_store_dwordx4 v[150:151], v[26:29], off offset:16
	global_store_dwordx4 v[150:151], v[22:25], off offset:512
	global_store_dwordx4 v[150:151], v[18:21], off offset:528
	s_waitcnt vmcnt(8)
	v_pk_add_f32 v[14:15], v[14:15], v[196:197]
	v_pk_add_f32 v[16:17], v[16:17], v[198:199]
	v_pk_add_f32 v[10:11], v[10:11], v[200:201]
	v_pk_add_f32 v[12:13], v[12:13], v[202:203]
	v_pk_add_f32 v[6:7], v[6:7], v[204:205]
	v_pk_add_f32 v[8:9], v[8:9], v[206:207]
	v_pk_add_f32 v[2:3], v[2:3], v[208:209]
	v_pk_add_f32 v[4:5], v[4:5], v[210:211]
	global_store_dwordx4 v[228:229], v[14:17], off
	global_store_dwordx4 v[228:229], v[10:13], off offset:16
	global_store_dwordx4 v[228:229], v[6:9], off offset:512
	global_store_dwordx4 v[228:229], v[2:5], off offset:528
	s_mov_b32 s1, 0x160000
	s_and_b64 vcc, exec, s[38:39]
	s_mov_b64 s[26:27], s[40:41]
	s_cbranch_vccz .LBB0_1027
	s_waitcnt vmcnt(0)
	v_readlane_b32 s52, v254, 26
	v_readlane_b32 s50, v254, 28
	s_mov_b64 s[58:59], s[84:85]
	s_cmpk_gt_u32 s4, 0xff
	v_readlane_b32 s53, v254, 27
	v_readlane_b32 s51, v254, 29
	s_cbranch_scc1 .LBB0_1038
	s_barrier
